# workspace pointer kept in two spare lanes of the SGPR-spill VGPR and read back with v_readlane instead of 43 kernarg SMEM reloads, on top of v35
# speedup vs baseline: 1.0211x; 1.0013x over previous
; #define LAS __attribute__((address_space(3)))
; DI cfp_t inp(int i) {
;   asm volatile("" : "+s"(i));
;   return ((const __attribute__((address_space(4))) cfp_t*)__builtin_amdgcn_kernarg_segment_ptr())[i];
; }
; DI unsigned char* wsp() { return (unsigned char*)inp(25); }
; __global__ void __launch_bounds__(512, 2) mega(Params p) {
;   cg::grid_group grid = cg::this_grid();
;   const int nb = gridDim.x, bid = blockIdx.x, t = threadIdx.x;
;   if (wsp() == nullptr) grid.sync();
;   volatile LAS unsigned* xst = (volatile LAS unsigned*)(smem + SMEM_MAIN);
;   if (t < 4) xst[t] = 0u;
_Z4mega6Params:
	s_mov_b64 s[70:71], s[0:1]
	s_load_dwordx2 s[0:1], s[70:71], 0xd0
	s_load_dword s33, s[70:71], 0xd8
	v_and_b32_e32 v224, 0x3ff, v0
	v_writelane_b32 v252, s2, 0
	s_add_u32 s2, s70, 0xd0
	s_waitcnt lgkmcnt(0)
	v_writelane_b32 v252, s0, 1
	s_addc_u32 s3, s71, 0
	s_nop 0
	v_writelane_b32 v252, s1, 2
	s_mov_b32 s0, 25
	s_ashr_i32 s1, s0, 31
	s_lshl_b64 s[0:1], s[0:1], 3
	s_add_u32 s0, s70, s0
	s_addc_u32 s1, s71, s1
	s_load_dwordx2 s[4:5], s[0:1], 0x0
	s_movk_i32 s0, 0x3ff
	s_waitcnt lgkmcnt(0)
	v_writelane_b32 v255, s4, 60
	v_writelane_b32 v255, s5, 61
	s_cmp_lg_u64 s[4:5], 0
	s_cbranch_scc0 .LBB0_129
	v_cmp_gt_u32_e32 vcc, 4, v224
	s_and_saveexec_b64 s[0:1], vcc

; #define LAS __attribute__((address_space(3)))
; DI unsigned xb_add(unsigned* p, unsigned v) { return __hip_atomic_fetch_add(p, v, __ATOMIC_RELAXED, __HIP_MEMORY_SCOPE_AGENT); }
; #define G_WS (wsp())
; DI unsigned xb_xcc_id() { return (unsigned)__builtin_amdgcn_s_getreg((3 << 11) | 20) & 0xFu; }
; DI XcdBarrier xcd_barrier_post(unsigned* bar, volatile LAS unsigned* st) {
;   XcdBarrier b; b.bar = bar; b.x = xb_xcc_id(); b.st = st;
;   if (threadIdx.x == 0) (void)xb_add(&bar[XB_XCNT(b.x)], 1u);
;   return b;
; __global__ void __launch_bounds__(512, 2) mega(Params p) {
;     ...
;   volatile LAS unsigned* xst = (volatile LAS unsigned*)(smem + SMEM_MAIN);
;   if (t < 4) xst[t] = 0u;
;   __syncthreads();
;   const XcdBarrier xbar = xcd_barrier_post((unsigned*)(G_WS + OFF_BAR), xst);
.LBB0_3:
	s_or_b64 exec, exec, s[0:1]
	s_mov_b32 s0, 25
	s_waitcnt lgkmcnt(0)
	s_barrier
	s_ashr_i32 s1, s0, 31
	s_lshl_b64 s[0:1], s[0:1], 3
	s_add_u32 s0, s70, s0
	s_addc_u32 s1, s71, s1
	v_readlane_b32 s2, v255, 60
	v_readlane_b32 s3, v255, 61
	s_nop 3
	s_getreg_b32 s0, hwreg(HW_REG_XCC_ID, 0, 4)
	s_mov_b32 s4, 25
	s_mov_b32 s6, 0
	v_cmp_eq_u32_e64 s[8:9], 0, v224
	s_waitcnt lgkmcnt(0)
	s_add_u32 s10, s2, 0xf8e2000
	s_addc_u32 s11, s3, 0
	s_and_b32 s40, s0, 15
	v_writelane_b32 v255, s40, 59
	s_mov_b32 s100, 2
	s_nop 0
	v_writelane_b32 v255, s100, 56
	s_mov_b64 s[0:1], exec
	v_writelane_b32 v252, s8, 3
	s_nop 1
	v_writelane_b32 v252, s9, 4
	s_and_b64 s[8:9], s[0:1], s[8:9]
	s_mov_b64 exec, s[8:9]
	s_cbranch_execz .LBB0_6
	s_mov_b64 s[8:9], exec
	v_mbcnt_lo_u32_b32 v0, s8, 0
	v_mbcnt_hi_u32_b32 v0, s9, v0
	v_cmp_eq_u32_e32 vcc, 0, v0
	s_and_b64 s[12:13], exec, vcc
	s_mov_b64 exec, s[12:13]
	s_cbranch_execz .LBB0_6
	s_lshl_b32 s5, s40, 8
	s_bcnt1_i32_b64 s7, s[8:9]
	v_mov_b32_e32 v0, s5
	v_mov_b32_e32 v1, s7
	global_atomic_add v0, v1, s[10:11] offset:1024
	v_readlane_b32 s100, v252, 0
	s_lshl_b32 s101, s40, 2
	s_and_b32 s100, s100, 63
	s_lshl_b32 s101, 1, s101
	s_lshl_b32 s100, s100, 2
	s_cmp_gt_u32 s40, 7
	s_cselect_b32 s101, 0, s101
	v_mov_b32_e32 v0, s100
	v_mov_b32_e32 v1, s101
	s_nop 0
	global_atomic_add v0, v1, s[10:11]

; DI int tid_opaque() { int t = threadIdx.x; asm volatile("" : "+v"(t)); return t; }
; DI double dpow(double c, int n) { double r = 1.0; for (int i = 0; i < n; ++i) r *= c; return r; }
; #define G_CS1 ((float2*)(wsp() + OFF_CS1))
; DI float2 cossin(double ang) {
;   double rev = ang * 0.15915494309189535;
;   rev -= rint(rev);
;   const float f = (float)rev;
;   float2 o;
;   o.x = __builtin_amdgcn_cosf(f);
;   o.y = __builtin_amdgcn_sinf(f);
;   return o;
; __global__ void __launch_bounds__(512, 2) mega(Params p) {
;     ...
;   for (int idx = bid * NT + tid_opaque(); idx < 163840; idx += nb * NT) {
;     if (idx < 65536) {
;       const int pos = idx >> 5, i = idx & 31;
;       G_CS1[idx] = cossin((double)pos * dpow(0.7498942093324559, i));
.LBB0_18:
	s_or_b64 exec, exec, s[30:31]
	s_mov_b32 s30, 25
	s_ashr_i32 s31, s30, 31
	v_ashrrev_i32_e32 v1, 5, v0
	s_lshl_b64 s[30:31], s[30:31], 3
	v_cvt_f64_i32_e32 v[10:11], v1
	s_add_u32 s30, s70, s30
	v_mul_f64 v[4:5], v[4:5], v[10:11]
	s_addc_u32 s31, s71, s31
	v_mul_f64 v[10:11], v[4:5], s[18:19]
	v_readlane_b32 s30, v255, 60
	v_readlane_b32 s31, v255, 61
	s_nop 3
	v_rndne_f64_e32 v[10:11], v[10:11]
	v_fma_f64 v[4:5], v[4:5], s[18:19], -v[10:11]
	v_cvt_f32_f64_e32 v1, v[4:5]
	v_cos_f32_e32 v2, v1
	v_sin_f32_e32 v9, v1
	v_ashrrev_i32_e32 v1, 31, v0
	s_waitcnt lgkmcnt(0)
	v_lshl_add_u64 v[10:11], v[0:1], 3, s[30:31]
	v_lshl_add_u64 v[4:5], v[10:11], 0, s[26:27]
	v_add_co_u32_e32 v10, vcc, 0xf7a2000, v10
	s_nop 1
	v_addc_co_u32_e32 v11, vcc, 0, v11, vcc
	global_store_dword v[10:11], v2, off

; DI double dpow(double c, int n) { double r = 1.0; for (int i = 0; i < n; ++i) r *= c; return r; }
; #define G_CSC ((float2*)(wsp() + OFF_CSC))
; DI float2 cossin(double ang) {
;   double rev = ang * 0.15915494309189535;
;   rev -= rint(rev);
;   const float f = (float)rev;
;   float2 o;
;   o.x = __builtin_amdgcn_cosf(f);
;   o.y = __builtin_amdgcn_sinf(f);
;   return o;
; __global__ void __launch_bounds__(512, 2) mega(Params p) {
;     ...
;     } else {
;       const int e = idx - 131072;
;       const int pos = e >> 4, i = e & 15;
;       G_CSC[e] = cossin((double)pos * dpow(0.5623413251903491, i));
.LBB0_26:
	s_or_b64 exec, exec, s[34:35]
	s_mov_b32 s34, 25
	v_add_u32_e32 v2, 0xfffe0000, v0
	s_ashr_i32 s35, s34, 31
	v_lshrrev_b32_e32 v1, 4, v2
	s_lshl_b64 s[34:35], s[34:35], 3
	v_cvt_f64_u32_e32 v[10:11], v1
	s_add_u32 s34, s70, s34
	v_mul_f64 v[4:5], v[4:5], v[10:11]
	s_addc_u32 s35, s71, s35
	v_mul_f64 v[10:11], v[4:5], s[18:19]
	v_readlane_b32 s34, v255, 60
	v_readlane_b32 s35, v255, 61
	s_nop 3
	v_rndne_f64_e32 v[10:11], v[10:11]
	v_fma_f64 v[4:5], v[4:5], s[18:19], -v[10:11]
	v_cvt_f32_f64_e32 v1, v[4:5]
	v_cos_f32_e32 v12, v1
	s_waitcnt lgkmcnt(0)
	v_lshl_add_u64 v[10:11], v[2:3], 3, s[34:35]
	v_lshl_add_u64 v[4:5], v[10:11], 0, s[20:21]
	v_add_co_u32_e32 v10, vcc, 0xf8a2000, v10
	v_sin_f32_e32 v9, v1
	s_nop 0
	v_addc_co_u32_e32 v11, vcc, 0, v11, vcc
	global_store_dword v[10:11], v12, off

; DI double dpow(double c, int n) { double r = 1.0; for (int i = 0; i < n; ++i) r *= c; return r; }
; #define G_CS2 ((float2*)(wsp() + OFF_CS2))
; DI float2 cossin(double ang) {
;   double rev = ang * 0.15915494309189535;
;   rev -= rint(rev);
;   const float f = (float)rev;
;   float2 o;
;   o.x = __builtin_amdgcn_cosf(f);
;   o.y = __builtin_amdgcn_sinf(f);
;   return o;
; __global__ void __launch_bounds__(512, 2) mega(Params p) {
;     ...
;     } else if (idx < 131072) {
;       const int e = idx - 65536;
;       const int pos = e >> 5, i = e & 31;
;       const double a = (i < 16) ? (double)(pos >> 6) * dpow(0.5623413251903491, i) : (double)(pos & 63) * dpow(0.5623413251903491, i - 16);
;       G_CS2[e] = cossin(a);
.LBB0_40:
	s_or_b64 exec, exec, s[34:35]
	s_mov_b32 s34, 25
	s_ashr_i32 s35, s34, 31
	s_lshl_b64 s[34:35], s[34:35], 3
	s_add_u32 s34, s70, s34
	s_addc_u32 s35, s71, s35
	v_mul_f64 v[10:11], v[4:5], s[18:19]
	v_readlane_b32 s34, v255, 60
	v_readlane_b32 s35, v255, 61
	s_nop 3
	v_rndne_f64_e32 v[10:11], v[10:11]
	v_fma_f64 v[4:5], v[4:5], s[18:19], -v[10:11]
	v_cvt_f32_f64_e32 v1, v[4:5]
	v_cos_f32_e32 v12, v1
	v_sin_f32_e32 v9, v1
	s_waitcnt lgkmcnt(0)
	v_lshl_add_u64 v[10:11], v[2:3], 3, s[34:35]
	v_lshl_add_u64 v[4:5], v[10:11], 0, s[22:23]
	v_add_co_u32_e32 v10, vcc, 0xf822000, v10
	s_nop 1
	v_addc_co_u32_e32 v11, vcc, 0, v11, vcc
	global_store_dword v[10:11], v12, off

; #define G_WS (wsp())
; #define G_CS1 ((float2*)(wsp() + OFF_CS1))
; #define G_CS2 ((float2*)(wsp() + OFF_CS2))
; #define G_CSC ((float2*)(wsp() + OFF_CSC))
; __global__ void __launch_bounds__(512, 2) mega(Params p) {
;     ...
;   for (int L = 0; L < 4; ++L) {
;     const int j = L >> 1;
;     const bool odd = (L & 1) != 0;
;     const bf16_t* wb = (const bf16_t*)(G_WS + OFF_W) + (size_t)(L & 1) * WSZ;
;     Ep e{};
;     e.cs1 = G_CS1; e.cs2 = G_CS2; e.csc = G_CSC;
.LBB0_184:
	s_lshr_b32 s6, s1, 1
	s_and_b32 s3, s1, 1
	s_cmp_eq_u32 s3, 0
	s_mov_b32 s0, 25
	v_writelane_b32 v254, s1, 41
	s_cselect_b64 s[40:41], -1, 0
	s_ashr_i32 s1, s0, 31
	s_lshl_b64 s[0:1], s[0:1], 3
	s_add_u32 s0, s70, s0
	s_addc_u32 s1, s71, s1
	v_readlane_b32 s4, v255, 60
	v_readlane_b32 s5, v255, 61
	s_nop 3
	s_mul_i32 s0, s3, 0x1b20000
	s_mov_b32 s2, 25
	s_waitcnt lgkmcnt(0)
	s_add_u32 s0, s4, s0
	v_writelane_b32 v254, s4, 42
	s_addc_u32 s1, s5, 0
	s_add_u32 s0, s0, 0xc000000
	v_writelane_b32 v254, s5, 43
	v_writelane_b32 v254, s0, 44
	s_addc_u32 s0, s1, 0
	v_writelane_b32 v254, s0, 45
	s_mov_b32 s0, 25
	s_mov_b32 s4, 25
	s_ashr_i32 s5, s4, 31
	s_lshl_b64 s[4:5], s[4:5], 3
	s_add_u32 s4, s70, s4
	s_addc_u32 s5, s71, s5
	v_readlane_b32 s4, v255, 60
	v_readlane_b32 s5, v255, 61
	s_nop 3
	v_writelane_b32 v254, s8, 46
	s_nop 1
	v_writelane_b32 v254, s9, 47
	v_cndmask_b32_e64 v0, 0, 1, s[8:9]
	s_waitcnt lgkmcnt(0)
	s_add_u32 s8, s4, 0xf8a2000
	s_addc_u32 s9, s5, 0
	s_cmp_eq_u32 s3, 1
	s_cselect_b64 s[38:39], -1, 0
	v_readfirstlane_b32 s1, v0
	s_and_b64 s[4:5], s[38:39], exec
	s_movk_i32 s3, 0x180
	s_cselect_b32 s7, 0x200, s3
	v_readlane_b32 s3, v252, 0
	s_mul_i32 s1, s1, 0x1b20000
	s_cmp_ge_i32 s3, s7
	v_writelane_b32 v254, s1, 48
	s_cbranch_scc1 .LBB0_263
	s_ashr_i32 s3, s2, 31
	s_lshl_b64 s[2:3], s[2:3], 3
	s_add_u32 s2, s70, s2
	s_addc_u32 s3, s71, s3
	s_load_dwordx2 s[2:3], s[2:3], 0x0
	v_readlane_b32 s12, v254, 35
	v_readlane_b32 s4, v254, 48
	v_readlane_b32 s33, v252, 0
	v_readlane_b32 s24, v254, 17
	s_waitcnt lgkmcnt(0)
	s_add_u32 s42, s2, 0xf7a2000
	s_addc_u32 s43, s3, 0
	s_ashr_i32 s1, s0, 31
	s_lshl_b64 s[0:1], s[0:1], 3
	s_add_u32 s0, s70, s0
	s_addc_u32 s1, s71, s1
	s_load_dwordx2 s[0:1], s[0:1], 0x0
	v_readlane_b32 s2, v254, 42
	v_readlane_b32 s3, v254, 43
	s_mov_b32 s25, s33
	v_readlane_b32 s13, v254, 36
	s_waitcnt lgkmcnt(0)
	s_add_u32 s44, s0, 0xf822000
	s_addc_u32 s45, s1, 0
	s_lshl_b32 s0, s6, 6
	s_mov_b32 s1, s12
	s_add_u32 s46, s2, s4
	s_addc_u32 s47, s3, 0
	s_lshl_b64 s[48:49], s[0:1], 2
	v_readlane_b32 s14, v254, 37
	v_readlane_b32 s15, v254, 38
	s_branch .LBB0_188

; #define BAR8 __builtin_amdgcn_s_barrier()
; #define G_SS ((float*)(wsp() + OFF_SS))
;     ...
;   if (!pre) {
;     STAGE8(SB8(0, 0), Bt, K, bcol, 0); STAGE8(SA8(0, 0), A, lda, brow, 0);
;     STAGE8(SB8(0, 1), Bt, K, bcol + 128, 0); STAGE8(SA8(0, 1), A, lda, brow + 128, 0);
;   }
;   if (wr == 1) BAR8;
; __global__ void __launch_bounds__(512, 2) mega(Params p) {
;     ...
;       for (int item = bid; item < nin; item += nb) {
;         const int nt = item >> 6, mt = item & 63;
;         e.ss = G_SS; e.nss = 16; e.inv_n = 1.f / 1024.f; e.out = G_ZB; e.ldo = ZLD;
;         if (!odd) {
;           e.g_a = inp(4) + j * 64; e.g_b = inp(5) + j * 64;
;           gemm_tile<EPI_IN_AB, 256, true>(G_XB, DM, wb + W_IN, DM, mt * 256, nt * 256, e);
.LBB0_188:
	s_and_b32 s0, s25, 63
	s_lshl_b32 s30, s0, 19
	s_and_b32 s0, s24, 0xffffff00
	s_ashr_i32 s1, s0, 31
	s_lshl_b64 s[56:57], s[0:1], 11
	s_mov_b32 s0, 25
	s_ashr_i32 s1, s0, 31
	s_and_b32 s20, s33, 63
	s_lshl_b64 s[0:1], s[0:1], 3
	s_add_u32 s0, s70, s0
	s_addc_u32 s1, s71, s1
	v_readlane_b32 s0, v255, 60
	v_readlane_b32 s1, v255, 61
	s_nop 3
	v_readlane_b32 s12, v254, 35
	s_mov_b32 s31, s12
	v_readlane_b32 s13, v254, 36
	v_readlane_b32 s14, v254, 37
	s_waitcnt lgkmcnt(0)
	s_add_u32 s54, s0, 0xf640000
	s_mov_b32 s0, 25
	s_addc_u32 s55, s1, 0
	s_ashr_i32 s1, s0, 31
	s_lshl_b64 s[0:1], s[0:1], 3
	s_add_u32 s0, s70, s0
	s_addc_u32 s1, s71, s1
	v_readlane_b32 s0, v255, 60
	v_readlane_b32 s1, v255, 61
	s_nop 3
	v_readlane_b32 s15, v254, 38
	s_waitcnt lgkmcnt(0)
	s_add_u32 s50, s0, 0x2000000
	s_addc_u32 s51, s1, 0
	s_lshl_b32 s0, s33, 2
	s_lshl_b32 s36, s20, 8
	s_and_b32 s52, s0, 0xffffff00
	s_andn2_b64 vcc, exec, s[40:41]
	s_mov_b64 s[0:1], -1
	s_cbranch_vccnz .LBB0_238
	s_mov_b32 s0, 4
	s_ashr_i32 s1, s0, 31
	s_lshl_b64 s[0:1], s[0:1], 3
	s_add_u32 s0, s70, s0
	s_addc_u32 s1, s71, s1
	s_mov_b32 s2, 5
	s_load_dwordx2 s[0:1], s[0:1], 0x0
	s_ashr_i32 s3, s2, 31
	s_lshl_b64 s[2:3], s[2:3], 3
	s_add_u32 s2, s70, s2
	s_addc_u32 s3, s71, s3
	s_mov_b32 s4, 25
	s_load_dwordx2 s[2:3], s[2:3], 0x0
	s_ashr_i32 s5, s4, 31
	s_lshl_b64 s[4:5], s[4:5], 3
	s_add_u32 s4, s70, s4
	s_addc_u32 s5, s71, s5
	v_mov_b32_e32 v3, v224
	v_readlane_b32 s12, v255, 60
	v_readlane_b32 s13, v255, 61
	s_nop 3
	s_ashr_i32 s53, s52, 31
	v_bfe_i32 v1, v3, 27, 1
	s_waitcnt vmcnt(10)
	v_lshlrev_b32_e32 v150, 4, v3
	v_lshrrev_b32_e32 v1, 22, v1
	v_add_u32_e32 v1, v150, v1
	v_and_b32_e32 v1, 0xfffffc00, v1
	v_ashrrev_i32_e32 v0, 31, v3
	v_sub_u32_e32 v1, v150, v1
	v_lshrrev_b32_e32 v0, 26, v0
	v_lshrrev_b32_e32 v5, 4, v1
	v_add_u32_e32 v0, v3, v0
	v_bitop3_b32 v5, v5, v1, 32 bitop3:0x6c
	v_ashrrev_i32_e32 v1, 31, v1
	v_ashrrev_i32_e32 v0, 6, v0
	v_lshrrev_b32_e32 v1, 26, v1
	v_lshlrev_b32_e32 v6, 3, v0
	v_add_u32_e32 v1, v5, v1
	v_and_b32_e32 v6, -16, v6
	v_ashrrev_i32_e32 v1, 6, v1
	v_add_u32_e32 v6, v1, v6
	v_mul_i32_i24_e32 v1, 64, v1
	v_lshlrev_b32_e32 v0, 5, v0
	v_sub_u32_e32 v1, v5, v1
	v_mov_b32_e32 v14, 1
	s_waitcnt vmcnt(9)
	v_add_u32_e32 v155, 0x2000, v150
	s_lshl_b64 s[4:5], s[52:53], 11
	v_readlane_b32 s21, v254, 44
	v_and_b32_e32 v0, 32, v0
	v_ashrrev_i16_sdwa v1, v14, sext(v1) dst_sel:DWORD dst_unused:UNUSED_PAD src0_sel:DWORD src1_sel:BYTE_0
	v_ashrrev_i32_e32 v5, 31, v155
	s_add_u32 s4, s21, s4
	v_readlane_b32 s27, v254, 45
	v_add_u32_sdwa v0, v0, sext(v1) dst_sel:DWORD dst_unused:UNUSED_PAD src0_sel:DWORD src1_sel:WORD_0
	v_ashrrev_i32_e32 v7, 31, v6
	v_lshrrev_b32_e32 v5, 22, v5
	s_addc_u32 s5, s27, s5
	v_lshlrev_b64 v[132:133], 11, v[6:7]
	v_ashrrev_i32_e32 v1, 31, v0
	v_add_u32_e32 v5, v155, v5
	v_lshl_add_u64 v[8:9], s[4:5], 0, v[132:133]
	v_lshlrev_b64 v[6:7], 1, v[0:1]
	v_ashrrev_i32_e32 v5, 10, v5
	v_lshl_add_u64 v[10:11], v[8:9], 0, v[6:7]
	v_mul_i32_i24_e32 v8, 0x400, v5
	v_sub_u32_e32 v8, v155, v8
	v_lshrrev_b32_e32 v9, 4, v8
	v_bitop3_b32 v9, v9, v8, 32 bitop3:0x6c
	v_ashrrev_i32_e32 v12, 31, v9
	v_lshrrev_b32_e32 v12, 26, v12
	v_add_u32_e32 v12, v9, v12
	v_lshlrev_b32_e32 v8, 3, v5
	v_ashrrev_i32_e32 v13, 6, v12
	v_and_b32_e32 v12, 0xc0, v12
	v_and_b32_e32 v8, -16, v8
	v_lshlrev_b32_e32 v5, 5, v5
	v_sub_u32_e32 v9, v9, v12
	v_add_u32_e32 v8, v13, v8
	v_and_b32_e32 v5, 32, v5
	v_ashrrev_i16_sdwa v9, v14, sext(v9) dst_sel:DWORD dst_unused:UNUSED_PAD src0_sel:DWORD src1_sel:BYTE_0
	v_add_u32_e32 v151, 0x10000, v150
	v_add_u32_sdwa v134, v5, sext(v9) dst_sel:DWORD dst_unused:UNUSED_PAD src0_sel:DWORD src1_sel:WORD_0
	v_ashrrev_i32_e32 v9, 31, v8
	v_readfirstlane_b32 s14, v151
	v_lshlrev_b64 v[136:137], 11, v[8:9]
	s_waitcnt vmcnt(8)
	v_add_u32_e32 v157, 0x12000, v150
	v_mov_b32_e32 v4, v2
	s_mov_b32 m0, s14
	v_lshl_add_u64 v[12:13], s[4:5], 0, v[136:137]
	v_readfirstlane_b32 s4, v157
	global_load_lds_dwordx4 v[10:11], off
	s_mov_b32 m0, s4
	s_lshl_b32 s4, s20, 19
	v_ashrrev_i32_e32 v135, 31, v134
	s_waitcnt lgkmcnt(0)
	s_add_u32 s4, s12, s4
	v_lshlrev_b64 v[8:9], 1, v[134:135]
	s_addc_u32 s5, s13, 0
	v_lshl_add_u64 v[12:13], v[12:13], 0, v[8:9]
	v_lshl_add_u64 v[14:15], s[4:5], 0, v[132:133]
	v_readfirstlane_b32 s14, v150
	s_or_b32 s58, s52, 0x80
	global_load_lds_dwordx4 v[12:13], off
	v_lshl_add_u64 v[14:15], v[14:15], 0, v[6:7]
	s_mov_b32 m0, s14
	v_readfirstlane_b32 s14, v155
	s_ashr_i32 s59, s58, 31
	global_load_lds_dwordx4 v[14:15], off
	s_mov_b32 m0, s14
	s_lshl_b64 s[14:15], s[58:59], 11
	s_add_u32 s14, s21, s14
	v_lshl_add_u64 v[16:17], s[4:5], 0, v[136:137]
	s_addc_u32 s15, s27, s15
	v_add_u32_e32 v160, 0x14000, v150
	v_lshl_add_u64 v[16:17], v[16:17], 0, v[8:9]
	v_lshl_add_u64 v[18:19], s[14:15], 0, v[132:133]
	v_readfirstlane_b32 s21, v160
	v_add_u32_e32 v161, 0x16000, v150
	global_load_lds_dwordx4 v[16:17], off
	v_lshl_add_u64 v[18:19], v[18:19], 0, v[6:7]
	s_mov_b32 m0, s21
	v_lshl_add_u64 v[20:21], s[14:15], 0, v[136:137]
	v_readfirstlane_b32 s14, v161
	global_load_lds_dwordx4 v[18:19], off
	s_mov_b32 m0, s14
	s_add_u32 s14, s4, 0x40000
	s_addc_u32 s15, s5, 0
	v_add_u32_e32 v162, 0x4000, v150
	v_lshl_add_u64 v[20:21], v[20:21], 0, v[8:9]
	v_lshl_add_u64 v[22:23], s[14:15], 0, v[132:133]
	v_readfirstlane_b32 s21, v162
	global_load_lds_dwordx4 v[20:21], off
	v_lshl_add_u64 v[22:23], v[22:23], 0, v[6:7]
	s_mov_b32 m0, s21
	v_add_u32_e32 v163, 0x6000, v150
	global_load_lds_dwordx4 v[22:23], off
	v_lshl_add_u64 v[22:23], s[14:15], 0, v[136:137]
	v_readfirstlane_b32 s14, v163
	v_lshl_add_u64 v[22:23], v[22:23], 0, v[8:9]
	s_mov_b32 m0, s14
	v_ashrrev_i32_e32 v5, 8, v3
	global_load_lds_dwordx4 v[22:23], off
	v_cmp_eq_u32_e32 vcc, 1, v5
	s_and_saveexec_b64 s[14:15], vcc
	s_cbranch_execz .LBB0_191
	s_barrier

; #define WAIT_V8(n) asm volatile("s_waitcnt vmcnt(" #n ")" ::: "memory")
; #define BAR8 __builtin_amdgcn_s_barrier()
; #define G_SSCQ ((float*)(wsp() + OFF_SSCQ))
; #define G_SSCKV ((float*)(wsp() + OFF_SSCKV))
;     ...
;     STAGE8(SB8(0, 0), Bt, K, bcol, 0); STAGE8(SA8(0, 0), A, lda, brow, 0);
;     STAGE8(SB8(0, 1), Bt, K, bcol + 128, 0); STAGE8(SA8(0, 1), A, lda, brow + 128, 0);
;   }
;   if (wr == 1) BAR8;
;   WAIT_V8(4); BAR8;
;   STAGE8(SB8(1, 0), Bt, K, bcol, 1); STAGE8(SA8(1, 0), A, lda, brow, 1); STAGE8(SB8(1, 1), Bt, K, bcol + 128, 1);
; __global__ void __launch_bounds__(512, 2) mega(Params p) {
;     ...
;         } else {
;           e.ss_cq = G_SSCQ; e.ss_ckv = G_SSCKV;
;           gemm_tile<EPI_IN_CD, 256, true>(G_XB, DM, wb + W_IN, DM, mt * 256, nt * 256, e);
.LBB0_238:
	s_and_b64 vcc, exec, s[0:1]
	s_cbranch_vccz .LBB0_187
	s_mov_b32 s0, 25
	s_ashr_i32 s1, s0, 31
	s_lshl_b64 s[0:1], s[0:1], 3
	s_add_u32 s0, s70, s0
	s_addc_u32 s1, s71, s1
	v_readlane_b32 s2, v255, 60
	v_readlane_b32 s3, v255, 61
	s_nop 3
	s_mov_b32 s0, 25
	s_ashr_i32 s1, s0, 31
	s_lshl_b64 s[0:1], s[0:1], 3
	s_add_u32 s0, s70, s0
	s_addc_u32 s1, s71, s1
	v_readlane_b32 s4, v255, 60
	v_readlane_b32 s5, v255, 61
	s_nop 3
	s_mov_b32 s0, 25
	s_ashr_i32 s1, s0, 31
	s_lshl_b64 s[0:1], s[0:1], 3
	s_add_u32 s0, s70, s0
	s_addc_u32 s1, s71, s1
	v_mov_b32_e32 v3, v224
	v_readlane_b32 s14, v255, 60
	v_readlane_b32 s15, v255, 61
	s_nop 3
	s_ashr_i32 s53, s52, 31
	v_bfe_i32 v1, v3, 27, 1
	s_waitcnt vmcnt(10)
	v_lshlrev_b32_e32 v150, 4, v3
	v_lshrrev_b32_e32 v1, 22, v1
	v_add_u32_e32 v1, v150, v1
	v_and_b32_e32 v1, 0xfffffc00, v1
	v_ashrrev_i32_e32 v0, 31, v3
	v_sub_u32_e32 v1, v150, v1
	v_lshrrev_b32_e32 v0, 26, v0
	v_lshrrev_b32_e32 v5, 4, v1
	v_add_u32_e32 v0, v3, v0
	v_bitop3_b32 v5, v5, v1, 32 bitop3:0x6c
	v_ashrrev_i32_e32 v1, 31, v1
	v_ashrrev_i32_e32 v0, 6, v0
	v_lshrrev_b32_e32 v1, 26, v1
	v_lshlrev_b32_e32 v6, 3, v0
	v_add_u32_e32 v1, v5, v1
	v_and_b32_e32 v6, -16, v6
	v_ashrrev_i32_e32 v1, 6, v1
	v_add_u32_e32 v6, v1, v6
	v_mul_i32_i24_e32 v1, 64, v1
	v_lshlrev_b32_e32 v0, 5, v0
	v_sub_u32_e32 v1, v5, v1
	v_mov_b32_e32 v14, 1
	s_waitcnt vmcnt(9)
	v_add_u32_e32 v155, 0x2000, v150
	s_lshl_b64 s[0:1], s[52:53], 11
	v_readlane_b32 s27, v254, 44
	v_and_b32_e32 v0, 32, v0
	v_ashrrev_i16_sdwa v1, v14, sext(v1) dst_sel:DWORD dst_unused:UNUSED_PAD src0_sel:DWORD src1_sel:BYTE_0
	v_ashrrev_i32_e32 v5, 31, v155
	s_add_u32 s0, s27, s0
	v_readlane_b32 s29, v254, 45
	v_add_u32_sdwa v0, v0, sext(v1) dst_sel:DWORD dst_unused:UNUSED_PAD src0_sel:DWORD src1_sel:WORD_0
	v_ashrrev_i32_e32 v7, 31, v6
	v_lshrrev_b32_e32 v5, 22, v5
	s_addc_u32 s1, s29, s1
	v_lshlrev_b64 v[132:133], 11, v[6:7]
	v_ashrrev_i32_e32 v1, 31, v0
	v_add_u32_e32 v5, v155, v5
	v_lshl_add_u64 v[8:9], s[0:1], 0, v[132:133]
	v_lshlrev_b64 v[6:7], 1, v[0:1]
	v_ashrrev_i32_e32 v5, 10, v5
	v_lshl_add_u64 v[10:11], v[8:9], 0, v[6:7]
	v_mul_i32_i24_e32 v8, 0x400, v5
	v_sub_u32_e32 v8, v155, v8
	v_lshrrev_b32_e32 v9, 4, v8
	v_bitop3_b32 v9, v9, v8, 32 bitop3:0x6c
	v_ashrrev_i32_e32 v12, 31, v9
	v_lshrrev_b32_e32 v12, 26, v12
	v_add_u32_e32 v12, v9, v12
	v_lshlrev_b32_e32 v8, 3, v5
	v_ashrrev_i32_e32 v13, 6, v12
	v_and_b32_e32 v12, 0xc0, v12
	v_and_b32_e32 v8, -16, v8
	v_lshlrev_b32_e32 v5, 5, v5
	v_sub_u32_e32 v9, v9, v12
	v_add_u32_e32 v8, v13, v8
	v_and_b32_e32 v5, 32, v5
	v_ashrrev_i16_sdwa v9, v14, sext(v9) dst_sel:DWORD dst_unused:UNUSED_PAD src0_sel:DWORD src1_sel:BYTE_0
	v_add_u32_e32 v151, 0x10000, v150
	v_add_u32_sdwa v134, v5, sext(v9) dst_sel:DWORD dst_unused:UNUSED_PAD src0_sel:DWORD src1_sel:WORD_0
	v_ashrrev_i32_e32 v9, 31, v8
	v_readfirstlane_b32 s12, v151
	v_lshlrev_b64 v[136:137], 11, v[8:9]
	s_waitcnt vmcnt(8)
	v_add_u32_e32 v158, 0x12000, v150
	v_mov_b32_e32 v4, v2
	s_mov_b32 m0, s12
	v_lshl_add_u64 v[12:13], s[0:1], 0, v[136:137]
	v_readfirstlane_b32 s0, v158
	global_load_lds_dwordx4 v[10:11], off
	s_mov_b32 m0, s0
	s_lshl_b32 s0, s20, 19
	v_ashrrev_i32_e32 v135, 31, v134
	s_waitcnt lgkmcnt(0)
	s_add_u32 s12, s14, s0
	v_lshlrev_b64 v[8:9], 1, v[134:135]
	s_addc_u32 s13, s15, 0
	v_lshl_add_u64 v[12:13], v[12:13], 0, v[8:9]
	v_lshl_add_u64 v[14:15], s[12:13], 0, v[132:133]
	v_readfirstlane_b32 s0, v150
	global_load_lds_dwordx4 v[12:13], off
	v_lshl_add_u64 v[14:15], v[14:15], 0, v[6:7]
	s_mov_b32 m0, s0
	v_readfirstlane_b32 s0, v155
	global_load_lds_dwordx4 v[14:15], off
	s_mov_b32 m0, s0
	s_or_b32 s0, s52, 0x80
	s_ashr_i32 s1, s0, 31
	s_lshl_b64 s[20:21], s[0:1], 11
	s_add_u32 s20, s27, s20
	v_lshl_add_u64 v[16:17], s[12:13], 0, v[136:137]
	s_addc_u32 s21, s29, s21
	v_add_u32_e32 v160, 0x14000, v150
	v_lshl_add_u64 v[16:17], v[16:17], 0, v[8:9]
	v_lshl_add_u64 v[18:19], s[20:21], 0, v[132:133]
	v_readfirstlane_b32 s1, v160
	v_lshl_add_u64 v[20:21], s[20:21], 0, v[136:137]
	v_add_u32_e32 v161, 0x16000, v150
	s_add_u32 s20, s12, 0x40000
	global_load_lds_dwordx4 v[16:17], off
	v_lshl_add_u64 v[18:19], v[18:19], 0, v[6:7]
	s_mov_b32 m0, s1
	v_readfirstlane_b32 s1, v161
	s_addc_u32 s21, s13, 0
	v_add_u32_e32 v162, 0x4000, v150
	global_load_lds_dwordx4 v[18:19], off
	v_lshl_add_u64 v[20:21], v[20:21], 0, v[8:9]
	s_mov_b32 m0, s1
	v_lshl_add_u64 v[22:23], s[20:21], 0, v[132:133]
	v_readfirstlane_b32 s1, v162
	global_load_lds_dwordx4 v[20:21], off
	v_lshl_add_u64 v[22:23], v[22:23], 0, v[6:7]
	s_mov_b32 m0, s1
	v_add_u32_e32 v163, 0x6000, v150
	global_load_lds_dwordx4 v[22:23], off
	v_lshl_add_u64 v[22:23], s[20:21], 0, v[136:137]
	v_readfirstlane_b32 s1, v163
	v_lshl_add_u64 v[22:23], v[22:23], 0, v[8:9]
	s_mov_b32 m0, s1
	v_ashrrev_i32_e32 v5, 8, v3
	global_load_lds_dwordx4 v[22:23], off
	v_cmp_eq_u32_e32 vcc, 1, v5
	s_and_saveexec_b64 s[20:21], vcc
	s_cbranch_execz .LBB0_241
	s_barrier

; DI unsigned char* wsp() { return (unsigned char*)inp(25); }
; DI void convert_layer(int L, int vb, int vnb) {
;   bf16_t* wb = (bf16_t*)(wsp() + OFF_W) + (size_t)(L & 1) * WSZ;
;   const int j = L >> 1;
;   int off = 0;
;   if ((L & 1) == 0) {
;     convert_mat(inp(3) + (size_t)j * 1024 * 1536, 1024, 1536, inp(2) + L * 1024, wb + W_IN, 0, off, vb, vnb, true);
;     convert_mat(inp(7) + (size_t)j * 1024 * 1024, 1024, 1024, nullptr, wb + W_OUT, 0, off, vb, vnb);
;   } else {
;     convert_mat(inp(8) + (size_t)j * 1024 * 1952, 1024, 1952, inp(2) + L * 1024, wb + W_IN, 1, off, vb, vnb, true);
; __global__ void __launch_bounds__(512, 2) mega(Params p) {
;     ...
;       if (L < 3) { if (odd || nb < 256) convert_layer(L + 1, bid, nb); else if (bid >= 128) convert_layer(L + 1, bid - 128, nb - 128); }
.LBB0_367:
	s_andn2_b64 vcc, exec, s[0:1]
	s_cbranch_vccnz .LBB0_490
	v_readlane_b32 s0, v254, 41
	s_add_i32 s30, s0, 1
	s_mov_b32 s0, 25
	s_ashr_i32 s1, s0, 31
	s_lshl_b64 s[0:1], s[0:1], 3
	s_add_u32 s0, s70, s0
	s_addc_u32 s1, s71, s1
	s_waitcnt lgkmcnt(0)
	v_readlane_b32 s2, v255, 60
	v_readlane_b32 s3, v255, 61
	s_nop 3
	s_and_b32 s0, s30, 1
	s_mul_i32 s0, s0, 0x1b20000
	v_readlane_b32 s44, v254, 35
	s_mov_b32 s43, s44
	s_waitcnt lgkmcnt(0)
	s_add_u32 s0, s2, s0
	s_addc_u32 s1, s3, 0
	s_add_u32 s40, s0, 0xc000000
	s_addc_u32 s41, s1, 0
	s_lshr_b32 s0, s30, 1
	s_bitcmp1_b32 s30, 0
	s_cselect_b64 s[12:13], -1, 0
	s_mov_b32 s1, s44
	s_lshl_b32 s42, s30, 10
	s_mov_b64 s[4:5], -1
	s_and_b64 vcc, exec, s[12:13]
	v_readlane_b32 s45, v254, 36
	v_readlane_b32 s46, v254, 37
	v_readlane_b32 s47, v254, 38
	s_cbranch_vccz .LBB0_417
	v_readlane_b32 s14, v253, 32
	v_readlane_b32 s15, v253, 33
	s_mov_b32 s12, 8
	s_mov_b32 s4, 2
	s_andn2_b64 vcc, exec, s[14:15]
	s_cbranch_vccnz .LBB0_382
	s_ashr_i32 s13, s12, 31
	s_lshl_b64 s[12:13], s[12:13], 3
	s_add_u32 s12, s70, s12
	s_addc_u32 s13, s71, s13
	s_load_dwordx2 s[12:13], s[12:13], 0x0
	s_mul_i32 s7, s0, 0x7a0000
	s_mul_hi_u32 s5, s0, 0x7a0000
	v_readlane_b32 s29, v252, 12
	s_waitcnt lgkmcnt(0)
	s_add_u32 s12, s12, s7
	s_addc_u32 s13, s13, s5
	s_ashr_i32 s5, s4, 31
	s_lshl_b64 s[4:5], s[4:5], 3
	s_add_u32 s4, s70, s4
	s_addc_u32 s5, s71, s5
	s_load_dwordx2 s[4:5], s[4:5], 0x0
	s_lshl_b64 s[14:15], s[42:43], 2
	s_waitcnt lgkmcnt(0)
	s_add_u32 s14, s4, s14
	s_addc_u32 s15, s5, s15
	s_cmp_lg_u64 s[4:5], 0
	v_readlane_b32 s4, v252, 1
	s_cselect_b64 s[20:21], -1, 0
	s_lshl_b32 s7, s29, 7
	s_lshl_b32 s27, s4, 7
	v_readlane_b32 s5, v252, 2
	s_branch .LBB0_372

; #define WAIT_V0() asm volatile("s_waitcnt vmcnt(0)" ::: "memory")
; #define G_SSCKV ((float*)(wsp() + OFF_SSCKV))
; template <int EPI, int BN, bool F16>
; DI void gemm_tile(const bf16_t* __restrict__ A, int lda, const bf16_t* __restrict__ W, int K, int m0, int n0, const Ep& e) {
;     ...
;   const int grow = w * 8 + (l >> 3);
;   const int gch = (l & 7) ^ ((grow >> 1) & 7);
;   const bf16_t* ap = A + (size_t)(m0 + grow) * lda + gch * 8;
;   const bf16_t* wp = W + (size_t)(n0 + grow) * K + gch * 8;
;   unsigned char* lbase = smem + w * 1024;
;   const int sw = (r >> 1) & 7;
;   const unsigned char* ab = smem + (wm * (MI * 32) + r) * 128;
;   const unsigned char* bb = smem + 32768 + (wn * 64 + r) * 128;
;   const int nk = K >> 6;
;     ...
;   G_STAGE(0, 0)
;   WAIT_V0();
;   __syncthreads();
;   for (int kt = 0; kt < nk; kt += 2) {
;     G_STAGE(1, kt + 1)
;     G_COMPUTE(0)
;     WAIT_V0();
;     __syncthreads();
;     if (kt + 2 < nk) { G_STAGE(0, kt + 2) }
;     G_COMPUTE(1)
;     WAIT_V0();
;     __syncthreads();
; __global__ void __launch_bounds__(512, 2) mega(Params p) {
;     ...
;           const int it = item - 192;
;           const int nt = it >> 6, mt = it & 63;
;           e.ss = G_SSCKV; e.nss = 2; e.inv_n = 1.f / 128.f; e.out = G_KVC; e.ldo = 1024;
;           gemm_tile<EPI_PLAIN, 128, false>(G_ZB + 256, ZLD, wb + W_UKV, 128, mt * 256, nt * 128, e);
.LBB0_547:
	s_cmpk_gt_i32 s33, 0xbf
	s_mov_b64 s[0:1], -1
	s_cbranch_scc0 .LBB0_551
	s_mov_b32 s12, 25
	s_mov_b32 s0, 25
	s_ashr_i32 s1, s0, 31
	s_lshl_b64 s[0:1], s[0:1], 3
	s_add_u32 s0, s70, s0
	s_addc_u32 s1, s71, s1
	v_readlane_b32 s2, v255, 60
	v_readlane_b32 s3, v255, 61
	s_nop 3
	s_mov_b32 s0, 25
	s_ashr_i32 s1, s0, 31
	s_lshl_b64 s[0:1], s[0:1], 3
	s_add_u32 s0, s70, s0
	s_addc_u32 s1, s71, s1
	v_mov_b32_e32 v0, v224
	v_readlane_b32 s14, v255, 60
	v_readlane_b32 s15, v255, 61
	s_nop 3
	s_and_b32 s0, s24, 0x7fffff80
	v_ashrrev_i32_e32 v3, 6, v0
	v_bfe_u32 v4, v0, 3, 3
	v_lshl_or_b32 v10, v3, 3, v4
	s_and_b32 s27, s25, 0x3f00
	s_addk_i32 s0, 0xfe80
	v_lshrrev_b32_e32 v4, 1, v10
	v_xor_b32_e32 v6, v4, v0
	v_add_u32_e32 v4, s27, v10
	v_add_u32_e32 v10, s0, v10
	v_ashrrev_i32_e32 v5, 31, v4
	v_ashrrev_i32_e32 v11, 31, v10
	v_lshlrev_b64 v[4:5], 12, v[4:5]
	v_lshlrev_b32_e32 v6, 4, v6
	v_lshlrev_b64 v[10:11], 8, v[10:11]
	s_waitcnt lgkmcnt(0)
	v_lshl_add_u64 v[4:5], s[14:15], 0, v[4:5]
	v_and_b32_e32 v6, 0x70, v6
	v_mov_b32_e32 v7, v2
	v_lshl_add_u64 v[10:11], s[4:5], 0, v[10:11]
	v_lshl_add_u64 v[4:5], v[4:5], 0, v[6:7]
	v_lshl_add_u64 v[6:7], v[10:11], 0, v[6:7]
	v_lshlrev_b32_e32 v10, 10, v3
	v_ashrrev_i32_e32 v3, 1, v0
	v_and_b32_e32 v1, 31, v0
	s_mov_b64 s[14:15], 0x2000200
	v_and_b32_e32 v3, 0xffffffc0, v3
	v_readfirstlane_b32 s1, v10
	v_lshl_add_u64 v[8:9], v[4:5], 0, s[14:15]
	v_or_b32_e32 v12, v3, v1
	s_mov_b32 m0, s1
	v_lshlrev_b32_e32 v69, 7, v12
	v_lshlrev_b32_e32 v12, 7, v0
	global_load_lds_dwordx4 v[8:9], off
	v_add_u32_e32 v8, 0x8000, v10
	v_and_b32_e32 v102, 0x2f80, v12
	v_readfirstlane_b32 s1, v8
	v_add_u32_e32 v12, 0x2000, v10
	s_mov_b32 m0, s1
	s_mov_b64 s[14:15], 0x2040200
	v_readfirstlane_b32 s1, v12
	v_add_u32_e32 v12, 0xa000, v10
	global_load_lds_dwordx4 v[6:7], off
	v_lshl_add_u64 v[8:9], v[4:5], 0, s[14:15]
	s_mov_b32 m0, s1
	s_mov_b64 s[14:15], 0x4000
	v_readfirstlane_b32 s1, v12
	v_add_u32_e32 v12, 0x4000, v10
	global_load_lds_dwordx4 v[8:9], off
	v_lshl_add_u64 v[8:9], v[6:7], 0, s[14:15]
	s_mov_b32 m0, s1
	s_mov_b64 s[14:15], 0x2080200
	v_readfirstlane_b32 s1, v12
	v_add_u32_e32 v12, 0x6000, v10
	global_load_lds_dwordx4 v[8:9], off
	v_lshl_add_u64 v[8:9], v[4:5], 0, s[14:15]
	s_mov_b32 m0, s1
	s_mov_b64 s[14:15], 0x20c0200
	v_readfirstlane_b32 s1, v12
	v_lshrrev_b32_e32 v11, 1, v0
	global_load_lds_dwordx4 v[8:9], off
	v_lshl_add_u64 v[8:9], v[4:5], 0, s[14:15]
	s_mov_b32 m0, s1
	v_bfe_u32 v68, v0, 5, 1
	global_load_lds_dwordx4 v[8:9], off
	v_bfe_u32 v103, v0, 1, 3
	v_add_u32_e32 v12, 0x10000, v10
	v_bitop3_b32 v8, v68, v11, 7 bitop3:0x78
	v_lshlrev_b32_e32 v104, 4, v8
	v_bitop3_b32 v8, v68, v103, 2 bitop3:0x36
	s_mov_b64 s[14:15], 0x2000280
	v_readfirstlane_b32 s1, v12
	v_add_u32_e32 v12, 0x18000, v10
	v_lshlrev_b32_e32 v105, 4, v8
	v_lshl_add_u64 v[8:9], v[4:5], 0, s[14:15]
	s_mov_b32 m0, s1
	s_mov_b64 s[14:15], 0x80
	v_readfirstlane_b32 s1, v12
	v_add_u32_e32 v12, 0x12000, v10
	s_waitcnt vmcnt(0)
	s_waitcnt vmcnt(0) lgkmcnt(0)
	s_barrier
	global_load_lds_dwordx4 v[8:9], off
	v_lshl_add_u64 v[8:9], v[6:7], 0, s[14:15]
	s_mov_b32 m0, s1
	s_mov_b64 s[14:15], 0x2040280
	v_readfirstlane_b32 s1, v12
	global_load_lds_dwordx4 v[8:9], off
	v_lshl_add_u64 v[8:9], v[4:5], 0, s[14:15]
	s_mov_b32 m0, s1
	s_mov_b64 s[14:15], 0x4080
	global_load_lds_dwordx4 v[8:9], off
	v_add_u32_e32 v8, 0x1a000, v10
	v_lshl_add_u64 v[6:7], v[6:7], 0, s[14:15]
	v_readfirstlane_b32 s1, v8
	v_add_u32_e32 v8, 0x14000, v10
	s_mov_b32 m0, s1
	s_mov_b64 s[14:15], 0x2080280
	v_readfirstlane_b32 s1, v8
	global_load_lds_dwordx4 v[6:7], off
	v_lshl_add_u64 v[6:7], v[4:5], 0, s[14:15]
	s_mov_b32 m0, s1
	s_mov_b64 s[14:15], 0x20c0280
	global_load_lds_dwordx4 v[6:7], off
	v_add_u32_e32 v6, 0x16000, v10
	v_lshl_add_u64 v[4:5], v[4:5], 0, s[14:15]
	v_readfirstlane_b32 s1, v6
	s_mov_b32 m0, s1
	v_or_b32_e32 v32, v69, v104
	global_load_lds_dwordx4 v[4:5], off
	v_or_b32_e32 v4, v102, v105
	v_or_b32_e32 v11, v69, v105
	ds_read_b128 v[70:73], v4 offset:36864
	ds_read_b128 v[74:77], v4 offset:32768
	v_or_b32_e32 v4, v102, v104
	ds_read_b128 v[78:81], v11 offset:4096
	ds_read_b128 v[82:85], v11
	ds_read_b128 v[20:23], v4 offset:36864
	ds_read_b128 v[24:27], v4 offset:32768
	ds_read_b128 v[28:31], v32 offset:4096
	s_waitcnt lgkmcnt(0)
	v_mfma_f32_32x32x16_bf16 v[4:19], v[28:31], v[24:27], 0
	ds_read_b128 v[32:35], v32
	s_movk_i32 s1, 0x100
	v_cmp_gt_i32_e32 vcc, s1, v0
	s_waitcnt lgkmcnt(0)
	v_mfma_f32_32x32x16_bf16 v[36:51], v[32:35], v[24:27], 0
	v_bitop3_b32 v24, v68, v103, 4 bitop3:0x36
	v_lshlrev_b32_e32 v106, 4, v24
	v_or_b32_e32 v24, v69, v106
	ds_read_b128 v[86:89], v24
	v_or_b32_e32 v98, v102, v106
	v_mfma_f32_32x32x16_bf16 v[52:67], v[32:35], v[20:23], 0
	ds_read_b128 v[90:93], v24 offset:4096
	v_mfma_f32_32x32x16_bf16 v[20:35], v[28:31], v[20:23], 0
	ds_read_b128 v[94:97], v98 offset:32768
	v_mfma_f32_32x32x16_bf16 v[36:51], v[82:85], v[74:77], v[36:51]
	ds_read_b128 v[98:101], v98 offset:36864
	v_mfma_f32_32x32x16_bf16 v[52:67], v[82:85], v[70:73], v[52:67]
	v_bitop3_b32 v82, v68, v103, 6 bitop3:0x36
	v_lshlrev_b32_e32 v103, 4, v82
	v_or_b32_e32 v107, v69, v103
	ds_read_b128 v[82:85], v107
	v_add_u32_e32 v69, 0x10000, v69
	v_mfma_f32_32x32x16_bf16 v[4:19], v[78:81], v[74:77], v[4:19]
	ds_read_b128 v[74:77], v107 offset:4096
	v_or_b32_e32 v107, v69, v104
	v_mfma_f32_32x32x16_bf16 v[20:35], v[78:81], v[70:73], v[20:35]
	v_or_b32_e32 v78, v102, v103
	ds_read_b128 v[70:73], v78 offset:32768
	v_or_b32_e32 v102, 0x18000, v102
	s_waitcnt lgkmcnt(0)
	v_mfma_f32_32x32x16_bf16 v[36:51], v[86:89], v[94:97], v[36:51]
	ds_read_b128 v[78:81], v78 offset:36864
	s_waitcnt vmcnt(0)
	s_waitcnt vmcnt(0) lgkmcnt(0)
	s_barrier
; #define WAIT_V0() asm volatile("s_waitcnt vmcnt(0)" ::: "memory")
; template <int EPI, int BN, bool F16>
; DI void gemm_tile(const bf16_t* __restrict__ A, int lda, const bf16_t* __restrict__ W, int K, int m0, int n0, const Ep& e) {
;     ...
;   for (int kt = 0; kt < nk; kt += 2) {
;     G_STAGE(1, kt + 1)
;     G_COMPUTE(0)
;     WAIT_V0();
;     __syncthreads();
;     if (kt + 2 < nk) { G_STAGE(0, kt + 2) }
;     G_COMPUTE(1)
;     WAIT_V0();
;     __syncthreads();
;   }
;     ...
;   if (t < 256) {
;     float rs = 1.f;
;     if (e.ss) {
;       const float* sp = e.ss + (size_t)(m0 + t) * e.nss;
;       float s = 0.f;
;       for (int i = 0; i < e.nss; ++i) s += sp[i];
;       rs = rsqrtf(s * e.inv_n + EPS);
;     }
;     ((float*)(smem + SMEM_RSTD))[t] = rs;
	v_mfma_f32_32x32x16_bf16 v[52:67], v[86:89], v[98:101], v[52:67]
	v_mfma_f32_32x32x16_bf16 v[4:19], v[90:93], v[94:97], v[4:19]
	ds_read_b128 v[94:97], v107 offset:4096
	v_mfma_f32_32x32x16_bf16 v[20:35], v[90:93], v[98:101], v[20:35]
	v_or_b32_e32 v98, v102, v104
	ds_read_b128 v[90:93], v98
	ds_read_b128 v[98:101], v98 offset:4096
	v_or_b32_e32 v104, v69, v105
	v_mfma_f32_32x32x16_bf16 v[20:35], v[74:77], v[78:81], v[20:35]
	s_waitcnt lgkmcnt(0)
	v_mfma_f32_32x32x16_bf16 v[20:35], v[94:97], v[98:101], v[20:35]
	v_mfma_f32_32x32x16_bf16 v[36:51], v[82:85], v[70:73], v[36:51]
	v_mfma_f32_32x32x16_bf16 v[52:67], v[82:85], v[78:81], v[52:67]
	v_or_b32_e32 v78, v102, v105
	v_mfma_f32_32x32x16_bf16 v[4:19], v[74:77], v[70:73], v[4:19]
	ds_read_b128 v[70:73], v104 offset:4096
	ds_read_b128 v[74:77], v78
	ds_read_b128 v[78:81], v78 offset:4096
	s_waitcnt lgkmcnt(0)
	v_mfma_f32_32x32x16_bf16 v[20:35], v[70:73], v[78:81], v[20:35]
	v_mfma_f32_32x32x16_bf16 v[4:19], v[94:97], v[90:93], v[4:19]
	v_mfma_f32_32x32x16_bf16 v[4:19], v[70:73], v[74:77], v[4:19]
	ds_read_b128 v[86:89], v107
	s_waitcnt lgkmcnt(0)
	v_mfma_f32_32x32x16_bf16 v[52:67], v[86:89], v[98:101], v[52:67]
	ds_read_b128 v[82:85], v104
	s_waitcnt lgkmcnt(0)
	v_mfma_f32_32x32x16_bf16 v[52:67], v[82:85], v[78:81], v[52:67]
	v_or_b32_e32 v78, v102, v106
	v_mfma_f32_32x32x16_bf16 v[36:51], v[86:89], v[90:93], v[36:51]
	v_mfma_f32_32x32x16_bf16 v[36:51], v[82:85], v[74:77], v[36:51]
	v_or_b32_e32 v82, v69, v106
	ds_read_b128 v[70:73], v82
	ds_read_b128 v[74:77], v78
	ds_read_b128 v[78:81], v78 offset:4096
	v_or_b32_e32 v69, v69, v103
	s_waitcnt lgkmcnt(1)
	v_mfma_f32_32x32x16_bf16 v[36:51], v[70:73], v[74:77], v[36:51]
	s_waitcnt lgkmcnt(0)
	v_mfma_f32_32x32x16_bf16 v[52:67], v[70:73], v[78:81], v[52:67]
	ds_read_b128 v[70:73], v82 offset:4096
	s_waitcnt lgkmcnt(0)
	v_mfma_f32_32x32x16_bf16 v[4:19], v[70:73], v[74:77], v[4:19]
	v_mfma_f32_32x32x16_bf16 v[20:35], v[70:73], v[78:81], v[20:35]
	ds_read_b128 v[70:73], v69
	v_or_b32_e32 v78, v102, v103
	ds_read_b128 v[74:77], v78
	ds_read_b128 v[78:81], v78 offset:4096
	s_waitcnt lgkmcnt(1)
	v_mfma_f32_32x32x16_bf16 v[36:51], v[70:73], v[74:77], v[36:51]
	s_waitcnt lgkmcnt(0)
	v_mfma_f32_32x32x16_bf16 v[52:67], v[70:73], v[78:81], v[52:67]
	ds_read_b128 v[70:73], v69 offset:4096
	s_waitcnt vmcnt(0)
	s_waitcnt lgkmcnt(0)
	s_barrier
	v_mfma_f32_32x32x16_bf16 v[4:19], v[70:73], v[74:77], v[4:19]
	v_mfma_f32_32x32x16_bf16 v[20:35], v[70:73], v[78:81], v[20:35]
	s_and_saveexec_b64 s[14:15], vcc
	s_cbranch_execz .LBB0_550
	s_ashr_i32 s13, s12, 31
	s_lshl_b64 s[12:13], s[12:13], 3
	s_add_u32 s12, s70, s12
	s_addc_u32 s13, s71, s13
	s_load_dwordx2 s[12:13], s[12:13], 0x0
	v_add_u32_e32 v70, s27, v0
	v_ashrrev_i32_e32 v71, 31, v70
	s_mov_b32 s1, 0xf782000
	s_waitcnt lgkmcnt(0)
	v_lshl_add_u64 v[70:71], v[70:71], 3, s[12:13]
	v_add_co_u32_e32 v70, vcc, s1, v70
	s_mov_b32 s1, 0x800000
	s_nop 0
	v_addc_co_u32_e32 v71, vcc, 0, v71, vcc
	global_load_dwordx2 v[70:71], v[70:71], off
	s_waitcnt vmcnt(0)
	v_add_f32_e32 v69, 0, v70
	v_add_f32_e32 v69, v69, v71
	v_mov_b32_e32 v70, 0x358637bd
	v_fmamk_f32 v69, v69, 0x3c000000, v70
	v_mul_f32_e32 v70, 0x4b800000, v69
	v_cmp_gt_f32_e32 vcc, s1, v69
	s_nop 1
	v_cndmask_b32_e32 v69, v69, v70, vcc
	v_rsq_f32_e32 v69, v69
	s_nop 0
	v_mul_f32_e32 v70, 0x45800000, v69
	v_cndmask_b32_e32 v69, v69, v70, vcc
	v_lshl_add_u32 v70, v0, 2, v234
	ds_write_b32 v70, v69

; #define WAIT_V8(n) asm volatile("s_waitcnt vmcnt(" #n ")" ::: "memory")
; #define BAR8 __builtin_amdgcn_s_barrier()
; #define G_SSCQ ((float*)(wsp() + OFF_SSCQ))
;     ...
;     STAGE8(SB8(0, 0), Bt, K, bcol, 0); STAGE8(SA8(0, 0), A, lda, brow, 0);
;     STAGE8(SB8(0, 1), Bt, K, bcol + 128, 0); STAGE8(SA8(0, 1), A, lda, brow + 128, 0);
;   }
;   if (wr == 1) BAR8;
;   WAIT_V8(4); BAR8;
;   STAGE8(SB8(1, 0), Bt, K, bcol, 1); STAGE8(SA8(1, 0), A, lda, brow, 1); STAGE8(SB8(1, 1), Bt, K, bcol + 128, 1);
; __global__ void __launch_bounds__(512, 2) mega(Params p) {
;     ...
;         if (item < 192) {
;           const int nt = item >> 6, mt = item & 63;
;           e.ss = G_SSCQ; e.nss = 4; e.inv_n = 1.f / 256.f; e.out = G_QC; e.ldo = 768;
;           gemm_tile<EPI_UQ, 256, false>(G_ZB, ZLD, wb + W_UQ, 256, mt * 256, nt * 256, e);
.LBB0_551:
	s_and_b64 vcc, exec, s[0:1]
	s_cbranch_vccz .LBB0_546
	s_mov_b32 s0, 25
	s_ashr_i32 s1, s0, 31
	s_lshl_b64 s[0:1], s[0:1], 3
	s_add_u32 s0, s70, s0
	s_addc_u32 s1, s71, s1
	v_readlane_b32 s2, v255, 60
	v_readlane_b32 s3, v255, 61
	s_nop 3
	s_mov_b32 s0, 25
	s_ashr_i32 s1, s0, 31
	s_lshl_b64 s[0:1], s[0:1], 3
	s_add_u32 s0, s70, s0
	s_addc_u32 s1, s71, s1
	s_mov_b32 s12, 25
	v_readlane_b32 s0, v255, 60
	v_readlane_b32 s1, v255, 61
	s_nop 3
	s_ashr_i32 s13, s12, 31
	s_lshl_b64 s[12:13], s[12:13], 3
	s_add_u32 s12, s70, s12
	s_addc_u32 s13, s71, s13
	v_mov_b32_e32 v3, v224
	v_readlane_b32 s12, v255, 60
	v_readlane_b32 s13, v255, 61
	s_nop 3
	s_and_b32 s30, s21, 0xffffff00
	v_bfe_i32 v1, v3, 27, 1
	v_lshlrev_b32_e32 v26, 4, v3
	v_lshrrev_b32_e32 v1, 22, v1
	v_add_u32_e32 v1, v26, v1
	v_and_b32_e32 v1, 0xfffffc00, v1
	v_ashrrev_i32_e32 v0, 31, v3
	v_sub_u32_e32 v1, v26, v1
	v_lshrrev_b32_e32 v0, 26, v0
	v_lshrrev_b32_e32 v5, 4, v1
	v_add_u32_e32 v0, v3, v0
	v_bitop3_b32 v5, v5, v1, 32 bitop3:0x6c
	v_ashrrev_i32_e32 v1, 31, v1
	v_ashrrev_i32_e32 v0, 6, v0
	v_lshrrev_b32_e32 v1, 26, v1
	v_lshlrev_b32_e32 v6, 3, v0
	v_add_u32_e32 v1, v5, v1
	v_and_b32_e32 v6, -16, v6
	v_ashrrev_i32_e32 v1, 6, v1
	v_add_u32_e32 v6, v1, v6
	v_mul_i32_i24_e32 v1, 64, v1
	s_ashr_i32 s31, s30, 31
	v_lshlrev_b32_e32 v0, 5, v0
	v_sub_u32_e32 v1, v5, v1
	v_mov_b32_e32 v13, 1
	v_add_u32_e32 v27, 0x2000, v26
	s_and_b32 s36, s25, 0x3f00
	s_lshl_b64 s[14:15], s[30:31], 9
	v_and_b32_e32 v0, 32, v0
	v_ashrrev_i16_sdwa v1, v13, sext(v1) dst_sel:DWORD dst_unused:UNUSED_PAD src0_sel:DWORD src1_sel:BYTE_0
	v_ashrrev_i32_e32 v5, 31, v27
	s_add_u32 s14, s7, s14
	v_add_u32_sdwa v0, v0, sext(v1) dst_sel:DWORD dst_unused:UNUSED_PAD src0_sel:DWORD src1_sel:WORD_0
	v_ashrrev_i32_e32 v7, 31, v6
	v_lshrrev_b32_e32 v5, 22, v5
	s_addc_u32 s15, s20, s15
	v_lshlrev_b64 v[16:17], 9, v[6:7]
	v_ashrrev_i32_e32 v1, 31, v0
	v_add_u32_e32 v5, v27, v5
	v_lshl_add_u64 v[8:9], s[14:15], 0, v[16:17]
	v_lshlrev_b64 v[0:1], 1, v[0:1]
	v_ashrrev_i32_e32 v5, 10, v5
	v_lshl_add_u64 v[14:15], v[8:9], 0, v[0:1]
	v_mul_i32_i24_e32 v8, 0x400, v5
	v_sub_u32_e32 v8, v27, v8
	v_lshrrev_b32_e32 v9, 4, v8
	v_bitop3_b32 v8, v9, v8, 32 bitop3:0x6c
	v_ashrrev_i32_e32 v10, 31, v8
	v_lshrrev_b32_e32 v10, 26, v10
	v_lshlrev_b32_e32 v9, 3, v5
	v_add_u32_e32 v10, v8, v10
	v_and_b32_e32 v9, -16, v9
	v_ashrrev_i32_e32 v11, 6, v10
	v_add_u32_e32 v12, v11, v9
	v_and_b32_e32 v9, 0xc0, v10
	v_sub_u32_e32 v8, v8, v9
	v_add_u32_e32 v30, 0x10000, v26
	v_ashrrev_i16_sdwa v8, v13, sext(v8) dst_sel:DWORD dst_unused:UNUSED_PAD src0_sel:DWORD src1_sel:BYTE_0
	v_ashrrev_i32_e32 v13, 31, v12
	v_readfirstlane_b32 s27, v30
	v_lshlrev_b64 v[18:19], 9, v[12:13]
	v_add_u32_e32 v33, 0x12000, v26
	v_mov_b32_e32 v4, v2
	s_mov_b32 m0, s27
	v_lshlrev_b32_e32 v5, 5, v5
	v_lshl_add_u64 v[10:11], s[14:15], 0, v[18:19]
	v_readfirstlane_b32 s14, v33
	global_load_lds_dwordx4 v[14:15], off
	v_and_b32_e32 v5, 32, v5
	s_mov_b32 m0, s14
	s_lshl_b32 s14, s36, 12
	v_add_u32_sdwa v8, v5, sext(v8) dst_sel:DWORD dst_unused:UNUSED_PAD src0_sel:DWORD src1_sel:WORD_0
	s_waitcnt lgkmcnt(0)
	s_add_u32 s27, s12, s14
	v_ashrrev_i32_e32 v9, 31, v8
	s_addc_u32 s29, s13, 0
	v_lshlrev_b64 v[8:9], 1, v[8:9]
	s_add_u32 s12, s27, 0x2000000
	v_lshl_add_u64 v[24:25], v[10:11], 0, v[8:9]
	s_addc_u32 s13, s29, 0
	v_lshlrev_b64 v[10:11], 12, v[6:7]
	v_lshl_add_u64 v[6:7], s[12:13], 0, v[10:11]
	v_readfirstlane_b32 s14, v26
	s_or_b32 s38, s30, 0x80
	global_load_lds_dwordx4 v[24:25], off
	v_lshl_add_u64 v[20:21], v[6:7], 0, v[0:1]
	s_mov_b32 m0, s14
	v_readfirstlane_b32 s14, v27
	s_ashr_i32 s39, s38, 31
	global_load_lds_dwordx4 v[20:21], off
	s_mov_b32 m0, s14
	s_lshl_b64 s[14:15], s[38:39], 9
	v_lshlrev_b64 v[12:13], 12, v[12:13]
	s_add_u32 s14, s7, s14
	v_lshl_add_u64 v[6:7], s[12:13], 0, v[12:13]
	s_addc_u32 s15, s20, s15
	v_add_u32_e32 v31, 0x14000, v26
	v_lshl_add_u64 v[22:23], v[6:7], 0, v[8:9]
	v_lshl_add_u64 v[6:7], s[14:15], 0, v[16:17]
	v_readfirstlane_b32 s37, v31
	v_add_u32_e32 v32, 0x16000, v26
	global_load_lds_dwordx4 v[22:23], off
	v_lshl_add_u64 v[16:17], v[6:7], 0, v[0:1]
	s_mov_b32 m0, s37
	v_lshl_add_u64 v[6:7], s[14:15], 0, v[18:19]
	v_readfirstlane_b32 s14, v32
	global_load_lds_dwordx4 v[16:17], off
	s_mov_b32 m0, s14
	s_add_u32 s14, s27, 0x2080000
	s_addc_u32 s15, s29, 0
	v_add_u32_e32 v28, 0x4000, v26
	v_lshl_add_u64 v[18:19], v[6:7], 0, v[8:9]
	v_lshl_add_u64 v[6:7], s[14:15], 0, v[10:11]
	v_readfirstlane_b32 s27, v28
	global_load_lds_dwordx4 v[18:19], off
	v_lshl_add_u64 v[6:7], v[6:7], 0, v[0:1]
	s_mov_b32 m0, s27
	v_add_u32_e32 v29, 0x6000, v26
	global_load_lds_dwordx4 v[6:7], off
	v_lshl_add_u64 v[6:7], s[14:15], 0, v[12:13]
	v_readfirstlane_b32 s14, v29
	v_lshl_add_u64 v[6:7], v[6:7], 0, v[8:9]
	s_mov_b32 m0, s14
	v_ashrrev_i32_e32 v132, 8, v3
	global_load_lds_dwordx4 v[6:7], off
	v_cmp_eq_u32_e32 vcc, 1, v132
	s_and_saveexec_b64 s[14:15], vcc
	s_cbranch_execz .LBB0_554
	s_barrier

; template <int DK, int DV, int MODE, int QB, bool PACK = false>
; DI void attn_item(const AttArgs& a, int q0, int t_lo, int t_hi) {
;     ...
;     for (int i = t; i < 465; i += NT) rpbs[i] = a.rpb[i];
; __global__ void __launch_bounds__(512, 2) mega(Params p) {
;     ...
;         const int qt = rest & 3, pg = rest >> 2;
;         const int pair = pg * 8 + pl;
;         const int b = pair >> 3, hd = pair & 7;
;         const int q0 = qt * 512;
;         const bf16_t* zrow = G_ZB + (size_t)b * SEQ * ZLD;
;         if (item < 256) {
;           a.q = G_QC + (size_t)b * SEQ * 768 + hd * 96; a.ldq = 768;
;           a.k = G_KVC + (size_t)b * SEQ * 1024 + hd * 128; a.ldk = 1024;
;           a.k2 = zrow + 384; a.ldk2 = ZLD;
;           a.v = G_KVC + (size_t)b * SEQ * 1024 + hd * 128 + 64; a.ldv = 1024;
;           a.o = G_OB + (size_t)b * SEQ * DM + hd * 64; a.ldo = DM;
;           a.scale = 0.10206207261596577f;
;           attn_item<96, 64, 3, 2>(a, q0, 0, 32);
;         } else {
;           a.q = zrow + 512 + hd * 64; a.k = zrow + 1024 + hd * 64; a.v = zrow + 1536 + hd * 64;
;           a.ldq = a.ldk = a.ldv = ZLD;
;           a.o = G_OB + (size_t)b * SEQ * DM + 512 + hd * 64; a.ldo = DM;
;           a.scale = 0.125f;
;           a.rpb = inp(13) + (size_t)(j * 8 + hd) * 465;
;           const int ra = q0 >> 6;
;           const int tlo = min(max(ra - 4, 0), 24), thi = min(max(ra + 7 - 4, 0), 24) + 8;
.LBB0_635:
	s_lshr_b32 s29, s25, 3
	s_and_b32 s38, s25, 7
	v_readlane_b32 s0, v254, 41
	s_bitcmp1_b32 s0, 0
	s_cselect_b64 s[2:3], -1, 0
	s_mov_b64 s[0:1], -1
	s_and_b64 vcc, exec, s[2:3]
	s_cbranch_vccz .LBB0_799
	s_lshl_b32 s0, s29, 9
	s_and_b32 s21, s0, 0x600
	s_mov_b32 s0, 25
	s_ashr_i32 s1, s0, 31
	s_lshl_b64 s[0:1], s[0:1], 3
	s_add_u32 s0, s70, s0
	s_addc_u32 s1, s71, s1
	v_readlane_b32 s0, v255, 60
	v_readlane_b32 s1, v255, 61
	s_nop 3
	s_lshl_b32 s2, s25, 6
	s_and_b32 s20, s2, 0x3800
	s_lshl_b32 s2, s20, 12
	v_writelane_b32 v254, s24, 52
	s_waitcnt lgkmcnt(0)
	s_add_u32 s0, s0, s2
	s_addc_u32 s1, s1, 0
	s_add_u32 s30, s0, 0x2000000
	s_addc_u32 s31, s1, 0
	v_writelane_b32 v254, s25, 53
	s_cmpk_gt_i32 s25, 0xff
	s_mov_b64 s[0:1], -1
	s_cbranch_scc0 .LBB0_752
	s_mov_b32 s0, 25
	s_ashr_i32 s1, s0, 31
	s_lshl_b64 s[0:1], s[0:1], 3
	s_add_u32 s0, s70, s0
	s_addc_u32 s1, s71, s1
	s_load_dwordx2 s[24:25], s[0:1], 0x0
	s_mov_b32 s2, 13
	v_mov_b32_e32 v0, v224
	s_movk_i32 s0, 0x1d1
	s_nop 0
	v_cmp_gt_i32_e32 vcc, s0, v0
	s_and_saveexec_b64 s[0:1], vcc
	s_cbranch_execz .LBB0_645
	s_ashr_i32 s3, s2, 31
	s_lshl_b64 s[2:3], s[2:3], 3
	s_add_u32 s2, s70, s2
	s_addc_u32 s3, s71, s3
	s_load_dwordx2 s[2:3], s[2:3], 0x0
	v_max_i32_e32 v1, 0xffffffd1, v0
	v_sub_u32_e32 v1, v1, v0
	v_add_u32_e32 v1, 0x1ff, v1
	s_movk_i32 s4, 0x1ff
	v_cmp_lt_u32_e32 vcc, s4, v1
	s_mov_b64 s[6:7], -1
	v_mov_b32_e32 v4, v0
	s_and_saveexec_b64 s[4:5], vcc
	s_cbranch_execz .LBB0_642
	v_readlane_b32 s6, v254, 49
	v_readlane_b32 s7, v254, 50
	s_or_b32 s6, s38, s6
	v_readlane_b32 s12, v254, 35
	v_lshrrev_b32_e32 v1, 9, v1
	s_mulk_i32 s6, 0x1d1
	s_mov_b32 s7, s12
	v_add_u32_e32 v3, 1, v1
	s_lshl_b64 s[6:7], s[6:7], 2
	s_waitcnt lgkmcnt(0)
	s_add_u32 s6, s2, s6
	v_and_b32_e32 v6, 0xfffffe, v3
	v_add_u32_e32 v1, 0x200, v0
	v_mov_b32_e32 v4, 0x9000
	s_addc_u32 s7, s3, s7
	v_lshl_add_u32 v7, v0, 2, v4
	s_mov_b64 s[8:9], 0
	v_mov_b32_e32 v8, v6
	v_mov_b64_e32 v[4:5], v[0:1]
	v_readlane_b32 s13, v254, 36
	v_readlane_b32 s14, v254, 37
	v_readlane_b32 s15, v254, 38

; template <int DK, int DV, int MODE>
; DI void att_gload(const AttArgs& a, int tile, u32x4 (&kr)[(64 * (DK / 8) + NT - 1) / NT], u32x4 (&vr)[(64 * (DV / 8) + NT - 1) / NT]) {
;     ...
; #pragma unroll
;   for (int i = 0; i < NKL; ++i) {
;     const int id = min(t + NT * i, 64 * CK - 1);
;     const int row = id / CK, c = id % CK;
;     if constexpr (MODE == 3) {
;       const bf16_t* src = (c < 8) ? (a.k + (size_t)(kbase + row) * a.ldk + c * 8) : (a.k2 + (size_t)(kbase + row) * a.ldk2 + (c - 8) * 8);
;       kr[i] = *(const u32x4*)src;
;     } else {
;       kr[i] = *(const u32x4*)(a.k + (size_t)(kbase + row) * a.ldk + c * 8);
;     }
;   }
; #pragma unroll
;   for (int i = 0; i < NVL; ++i) {
;     const int id = t + NT * i;
;     const int row = id / CV, c = id % CV;
;     vr[i] = *(const u32x4*)(a.v + (size_t)(kbase + row) * a.ldv + c * 8);
;   }
; template <int DK, int DV, int MODE, int QB, bool PACK = false>
; DI void attn_item(const AttArgs& a, int q0, int t_lo, int t_hi) {
;     ...
;   bf16x8 qf[QB][NKS];
; #pragma unroll
;   for (int qb = 0; qb < QB; ++qb) {
;     const bf16_t* qp = a.q + hg * DK + (size_t)(wq0 + qb * 32 + r) * a.ldq + h * 8;
; #pragma unroll
;     for (int s = 0; s < NKS; ++s) qf[qb][s] = *(const bf16x8*)(qp + s * 16);
;   }
.LBB0_752:
	s_and_b64 vcc, exec, s[0:1]
	s_cbranch_vccz .LBB0_798
	s_mov_b32 s0, 25
	s_ashr_i32 s1, s0, 31
	s_lshl_b64 s[0:1], s[0:1], 3
	s_add_u32 s0, s70, s0
	s_addc_u32 s1, s71, s1
	v_readlane_b32 s0, v255, 60
	v_readlane_b32 s1, v255, 61
	s_nop 3
	s_mul_i32 s3, s20, 0x600
	s_mul_i32 s4, s38, 0xc0
	s_mov_b32 s2, 25
	s_waitcnt lgkmcnt(0)
	s_add_u32 s0, s0, s3
	s_addc_u32 s1, s1, 0
	s_add_u32 s0, s0, s4
	s_addc_u32 s1, s1, 0
	s_ashr_i32 s3, s2, 31
	s_lshl_b64 s[2:3], s[2:3], 3
	s_add_u32 s2, s70, s2
	s_addc_u32 s3, s71, s3
	s_mov_b32 s4, 25
	s_mov_b32 s6, 25
	v_mov_b32_e32 v16, v224
	v_readlane_b32 s2, v255, 60
	v_readlane_b32 s3, v255, 61
	s_nop 3
	v_mov_b32_e32 v209, v2
	v_and_b32_e32 v0, 0xffffffc0, v16
	v_bfe_u32 v17, v16, 5, 1
	v_and_b32_e32 v3, 31, v16
	v_add_u32_e32 v0, s21, v0
	v_lshlrev_b32_e32 v208, 4, v17
	v_or_b32_e32 v206, v0, v3
	v_lshl_add_u64 v[0:1], s[0:1], 0, v[208:209]
	s_mov_b64 s[0:1], 0x8000000
	v_lshl_add_u64 v[0:1], v[0:1], 0, s[0:1]
	s_movk_i32 s5, 0x600
	v_or_b32_e32 v204, 32, v206
	v_mad_i64_i32 v[4:5], s[0:1], v206, s5, v[0:1]
	v_mad_i64_i32 v[0:1], s[0:1], v204, s5, v[0:1]
	global_load_dwordx4 v[188:191], v[4:5], off
	global_load_dwordx4 v[184:187], v[4:5], off offset:32
	global_load_dwordx4 v[180:183], v[4:5], off offset:64
	global_load_dwordx4 v[176:179], v[4:5], off offset:96
	global_load_dwordx4 v[172:175], v[4:5], off offset:128
	global_load_dwordx4 v[168:171], v[4:5], off offset:160
	global_load_dwordx4 v[164:167], v[0:1], off
	global_load_dwordx4 v[160:163], v[0:1], off offset:32
	global_load_dwordx4 v[156:159], v[0:1], off offset:64
	global_load_dwordx4 v[152:155], v[0:1], off offset:96
	global_load_dwordx4 v[148:151], v[0:1], off offset:128
	global_load_dwordx4 v[144:147], v[0:1], off offset:160
	s_lshl_b32 s0, s20, 11
	s_waitcnt lgkmcnt(0)
	s_add_u32 s0, s2, s0
	s_addc_u32 s1, s3, 0
	s_lshl_b32 s2, s38, 8
	s_add_u32 s0, s0, s2
	s_addc_u32 s1, s1, 0
	s_add_u32 s0, s0, 0x9800000
	s_addc_u32 s1, s1, 0
	s_ashr_i32 s5, s4, 31
	s_lshl_b64 s[2:3], s[4:5], 3
	s_add_u32 s2, s70, s2
	s_addc_u32 s3, s71, s3
	s_ashr_i32 s7, s6, 31
	v_mov_b32_e32 v12, v224
	s_lshl_b64 s[4:5], s[6:7], 3
	s_mov_b32 s6, 0x2aaaaaab
	v_min_i32_e32 v0, 0x2ff, v12
	v_mul_hi_i32 v1, v0, s6
	v_lshrrev_b32_e32 v4, 31, v1
	v_ashrrev_i32_e32 v1, 1, v1
	v_add_u32_e32 v4, v1, v4
	v_mul_lo_u32 v1, v4, 12
	s_add_u32 s4, s70, s4
	v_sub_u32_e32 v0, v0, v1
	s_addc_u32 s5, s71, s5
	v_cmp_lt_i32_e32 vcc, 7, v0
	v_ashrrev_i32_e32 v5, 31, v4
	v_lshlrev_b32_e32 v0, 3, v0
	s_and_saveexec_b64 s[6:7], vcc
	s_xor_b64 s[6:7], exec, s[6:7]
	v_lshlrev_b64 v[4:5], 12, v[4:5]
	v_lshl_add_u64 v[4:5], s[30:31], 0, v[4:5]
	v_mov_b32_e32 v1, v2
	v_lshl_add_u64 v[0:1], v[0:1], 1, v[4:5]
	s_mov_b64 s[8:9], 0x280
	v_lshl_add_u64 v[6:7], v[0:1], 0, s[8:9]
	s_or_saveexec_b64 s[6:7], s[6:7]
	s_load_dwordx2 s[2:3], s[2:3], 0x0
	s_nop 0
	s_load_dwordx2 s[4:5], s[4:5], 0x0
	s_xor_b64 exec, exec, s[6:7]
	v_lshlrev_b64 v[4:5], 11, v[4:5]
	v_lshl_add_u64 v[4:5], s[0:1], 0, v[4:5]
	v_ashrrev_i32_e32 v1, 31, v0
	v_lshl_add_u64 v[6:7], v[0:1], 1, v[4:5]
	s_or_b64 exec, exec, s[6:7]
	global_load_dwordx4 v[4:7], v[6:7], off
	v_min_i32_e32 v0, 0xff, v12
	v_add_u32_e32 v0, 0x200, v0
	s_mov_b32 s6, 0x2aaaaaab
	v_mul_hi_i32 v1, v0, s6
	v_lshrrev_b32_e32 v8, 31, v1
	v_ashrrev_i32_e32 v1, 1, v1
	v_add_u32_e32 v10, v1, v8
	v_mul_lo_u32 v1, v10, 12
	v_sub_u32_e32 v0, v0, v1
	v_cmp_lt_i32_e32 vcc, 7, v0
	v_ashrrev_i32_e32 v11, 31, v10
	v_lshlrev_b32_e32 v8, 3, v0
	s_and_saveexec_b64 s[6:7], vcc
	s_xor_b64 s[6:7], exec, s[6:7]
	v_lshlrev_b64 v[0:1], 12, v[10:11]
	v_lshl_add_u64 v[0:1], s[30:31], 0, v[0:1]
	v_mov_b32_e32 v9, v2
	v_lshl_add_u64 v[0:1], v[8:9], 1, v[0:1]
	s_mov_b64 s[8:9], 0x280
	v_lshl_add_u64 v[0:1], v[0:1], 0, s[8:9]
	s_andn2_saveexec_b64 s[6:7], s[6:7]
	v_lshlrev_b64 v[0:1], 11, v[10:11]
	v_lshl_add_u64 v[0:1], s[0:1], 0, v[0:1]
	v_ashrrev_i32_e32 v9, 31, v8
	v_lshl_add_u64 v[0:1], v[8:9], 1, v[0:1]
	s_or_b64 exec, exec, s[6:7]
	s_lshl_b32 s6, s20, 10
	s_lshl_b32 s12, s38, 7
	s_lshl_b32 s13, s6, 1
	s_waitcnt lgkmcnt(0)
	s_add_u32 s2, s2, s13
	global_load_dwordx4 v[8:11], v[0:1], off
	v_ashrrev_i32_e32 v0, 31, v12
	s_addc_u32 s3, s3, 0
	s_lshl_b32 s6, s12, 1
	v_lshrrev_b32_e32 v0, 29, v0
	s_add_u32 s2, s2, s6
	v_add_u32_e32 v1, v12, v0
	s_addc_u32 s3, s3, 0
	v_ashrrev_i32_e32 v0, 3, v1
	v_and_b32_e32 v1, 0x1ffffff8, v1
	s_add_u32 s2, s2, 0x9800080
	v_sub_u32_e32 v12, v12, v1
	v_ashrrev_i32_e32 v1, 31, v0
	s_addc_u32 s3, s3, 0
	v_lshlrev_b32_e32 v12, 3, v12
	v_lshlrev_b64 v[0:1], 11, v[0:1]
	v_ashrrev_i32_e32 v13, 31, v12
	v_lshl_add_u64 v[0:1], s[2:3], 0, v[0:1]
	v_lshl_add_u64 v[0:1], v[12:13], 1, v[0:1]
	global_load_dwordx4 v[12:15], v[0:1], off
	v_mov_b32_e32 v0, v224
	s_movk_i32 s6, 0x300
	s_nop 0
	v_cmp_gt_i32_e32 vcc, s6, v0
	s_and_saveexec_b64 s[6:7], vcc
	s_cbranch_execz .LBB0_763
	s_mov_b32 s8, 0x2aaaaaab
	v_mul_hi_i32 v1, v0, s8
	v_lshrrev_b32_e32 v18, 31, v1
	v_ashrrev_i32_e32 v1, 1, v1
	v_add_u32_e32 v1, v1, v18
	v_mul_lo_u32 v18, v1, 12
	s_movk_i32 s8, 0xd0
	v_sub_u32_e32 v18, v0, v18
	v_mul_lo_u32 v1, v1, s8
	v_lshl_add_u32 v1, v18, 4, v1
	s_waitcnt vmcnt(2)
	ds_write_b128 v1, v[4:7]

; template <int DK, int DV, int MODE>
; DI void att_gload(const AttArgs& a, int tile, u32x4 (&kr)[(64 * (DK / 8) + NT - 1) / NT], u32x4 (&vr)[(64 * (DV / 8) + NT - 1) / NT]) {
;     ...
; #pragma unroll
;   for (int i = 0; i < NKL; ++i) {
;     const int id = min(t + NT * i, 64 * CK - 1);
;     const int row = id / CK, c = id % CK;
;     if constexpr (MODE == 3) {
;       const bf16_t* src = (c < 8) ? (a.k + (size_t)(kbase + row) * a.ldk + c * 8) : (a.k2 + (size_t)(kbase + row) * a.ldk2 + (c - 8) * 8);
;       kr[i] = *(const u32x4*)src;
;     } else {
;       kr[i] = *(const u32x4*)(a.k + (size_t)(kbase + row) * a.ldk + c * 8);
;     }
;   }
; #pragma unroll
;   for (int i = 0; i < NVL; ++i) {
;     const int id = t + NT * i;
;     const int row = id / CV, c = id % CV;
;     vr[i] = *(const u32x4*)(a.v + (size_t)(kbase + row) * a.ldv + c * 8);
;   }
; __global__ void __launch_bounds__(512, 2) mega(Params p) {
;     ...
;           const int qtb = rest & 15, pgb = rest >> 4;
;           const int pairb = pgb * 8 + pl;
;           const int bb = pairb >> 1, kvb = pairb & 1;
;           const bf16_t* zrb = G_ZB + (size_t)bb * SEQ * ZLD;
;           a.q = zrb + 768 + kvb * 256; a.k = zrb + 1280 + kvb * 64; a.v = zrb + 1408 + kvb * 64;
;           a.o = G_OB + (size_t)bb * SEQ * DM + 512 + kvb * 256;
;           a.sinkp = inp(6) + j * 8 + kvb * 4;
;           const int q0b = qtb * 128;
;           const int tlo = max(q0b - 128, 0) >> 6, thi = min(q0b + 128 + 128, SEQ) >> 6;
;           attn_item<64, 64, 1, 2, true>(a, q0b, tlo, thi);
.LBB0_799:
	s_andn2_b64 vcc, exec, s[0:1]
	s_cbranch_vccnz .LBB0_634
	s_lshr_b32 s0, s25, 4
	s_and_b32 s0, s0, 8
	s_or_b32 s0, s0, s38
	s_and_b32 s13, s25, 1
	s_lshl_b32 s0, s0, 21
	s_bfe_u32 s15, s25, 0x40003
	s_lshl_b32 s14, s13, 2
	s_and_b32 s12, s0, 0x1c00000
	s_mov_b32 s8, 25
	s_cmpk_gt_i32 s25, 0xff
	s_mov_b64 s[0:1], -1
	s_cbranch_scc0 .LBB0_829
	s_mov_b32 s0, 25
	s_ashr_i32 s1, s0, 31
	s_lshl_b64 s[0:1], s[0:1], 3
	s_add_u32 s0, s70, s0
	s_addc_u32 s1, s71, s1
	v_readlane_b32 s0, v255, 60
	v_readlane_b32 s1, v255, 61
	s_nop 3
	s_lshl_b32 s3, s12, 1
	s_mov_b32 s2, 25
	v_mov_b32_e32 v3, v224
	s_waitcnt lgkmcnt(0)
	s_add_u32 s0, s0, s3
	s_addc_u32 s1, s1, 0
	s_add_u32 s0, s0, 0x2000000
	s_addc_u32 s1, s1, 0
	s_lshl_b32 s3, s13, 9
	s_add_u32 s4, s0, s3
	s_addc_u32 s5, s1, 0
	s_lshl_b32 s3, s13, 7
	s_add_u32 s30, s0, s3
	s_addc_u32 s31, s1, 0
	s_ashr_i32 s3, s2, 31
	s_lshl_b64 s[0:1], s[2:3], 3
	s_add_u32 s0, s70, s0
	s_mov_b32 s2, 6
	s_addc_u32 s1, s71, s1
	s_ashr_i32 s3, s2, 31
	s_lshl_b64 s[2:3], s[2:3], 3
	s_add_u32 s2, s70, s2
	s_addc_u32 s3, s71, s3
	s_lshl_b32 s6, s15, 7
	v_mov_b32_e32 v0, 0x80
	v_sub_u32_e64 v5, s6, v0 clamp
	v_ashrrev_i32_e32 v186, 7, v3
	v_and_b32_e32 v0, 64, v3
	v_lshlrev_b32_e32 v184, 6, v186
	v_bfe_u32 v187, v3, 5, 1
	v_and_b32_e32 v1, 31, v3
	v_or_b32_e32 v4, s6, v0
	v_ashrrev_i32_e32 v185, 31, v184
	v_lshl_add_u64 v[6:7], v[184:185], 1, s[4:5]
	v_or_b32_e32 v213, v4, v1
	v_lshlrev_b32_e32 v188, 4, v187
	v_mov_b32_e32 v189, v2
	v_lshl_add_u64 v[6:7], v[6:7], 0, v[188:189]
	v_lshlrev_b32_e32 v8, 12, v213
	v_mov_b32_e32 v9, v2
	v_lshl_add_u64 v[8:9], v[6:7], 0, v[8:9]
	v_or_b32_e32 v189, 32, v213
	global_load_dwordx4 v[144:147], v[8:9], off offset:1536
	global_load_dwordx4 v[148:151], v[8:9], off offset:1568
	global_load_dwordx4 v[152:155], v[8:9], off offset:1600
	global_load_dwordx4 v[156:159], v[8:9], off offset:1632
	v_lshlrev_b32_e32 v8, 12, v189
	v_mov_b32_e32 v9, v2
	v_lshl_add_u64 v[6:7], v[6:7], 0, v[8:9]
	v_mov_b32_e32 v10, v224
	global_load_dwordx4 v[160:163], v[6:7], off offset:1536
	global_load_dwordx4 v[164:167], v[6:7], off offset:1568
	global_load_dwordx4 v[168:171], v[6:7], off offset:1600
	global_load_dwordx4 v[172:175], v[6:7], off offset:1632
	s_movk_i32 s4, 0x1ff
	v_min_i32_e32 v6, 0x1ff, v10
	v_ashrrev_i32_e32 v7, 31, v6
	v_lshrrev_b32_e32 v7, 29, v7
	v_add_u32_e32 v7, v6, v7
	v_ashrrev_i32_e32 v8, 3, v7
	v_and_b32_e32 v7, 0x1ffffff8, v7
	v_sub_u32_e32 v9, v6, v7
	v_add_u32_e32 v6, v8, v5
	v_ashrrev_i32_e32 v7, 31, v6
	v_lshlrev_b32_e32 v8, 3, v9
	v_lshlrev_b64 v[6:7], 12, v[6:7]
	v_ashrrev_i32_e32 v9, 31, v8
	v_lshl_add_u64 v[6:7], s[30:31], 0, v[6:7]
	v_lshl_add_u64 v[6:7], v[8:9], 1, v[6:7]
	v_ashrrev_i32_e32 v8, 31, v10
	v_lshrrev_b32_e32 v8, 29, v8
	v_add_u32_e32 v8, v10, v8
	v_ashrrev_i32_e32 v9, 3, v8
	v_and_b32_e32 v8, 0x1ffffff8, v8
	v_sub_u32_e32 v10, v10, v8
	v_add_u32_e32 v8, v9, v5
	v_ashrrev_i32_e32 v9, 31, v8
	v_lshlrev_b32_e32 v10, 3, v10
	v_lshlrev_b64 v[8:9], 12, v[8:9]
	v_ashrrev_i32_e32 v11, 31, v10
	v_lshl_add_u64 v[8:9], s[30:31], 0, v[8:9]
	v_lshl_add_u64 v[8:9], v[10:11], 1, v[8:9]
	global_load_dwordx4 v[176:179], v[6:7], off offset:2560
	global_load_dwordx4 v[180:183], v[8:9], off offset:2816
	v_mov_b32_e32 v6, v224
	s_mov_b32 s72, s25
	s_mov_b32 s33, s24
	v_readfirstlane_b32 s7, v5
	s_nop 0
	v_cmp_lt_i32_e32 vcc, s4, v6
	s_and_saveexec_b64 s[4:5], vcc
	s_xor_b64 s[4:5], exec, s[4:5]
	v_lshrrev_b32_e32 v5, 3, v6
	s_movk_i32 s9, 0x90
	v_lshlrev_b32_e32 v6, 4, v6
	v_mul_lo_u32 v5, v5, s9
	v_and_b32_e32 v7, 0x70, v6
	s_or_saveexec_b64 s[4:5], s[4:5]
	s_load_dwordx2 s[68:69], s[0:1], 0x0
	s_load_dwordx2 s[66:67], s[2:3], 0x0
	s_xor_b64 exec, exec, s[4:5]
	s_cbranch_execz .LBB0_805
	v_ashrrev_i32_e32 v5, 31, v6
	v_lshrrev_b32_e32 v5, 29, v5
	v_add_u32_e32 v7, v6, v5
	v_lshrrev_b32_e32 v5, 3, v7
	v_and_b32_e32 v7, 0xffffff8, v7
	s_movk_i32 s0, 0x90
	v_sub_u32_e32 v6, v6, v7
	v_mul_lo_u32 v5, v5, s0
	v_lshlrev_b32_e32 v7, 4, v6
	v_add_u32_e32 v6, v5, v7
	s_waitcnt vmcnt(1)
	ds_write_b128 v6, v[176:179]

; #define WAIT_V8(n) asm volatile("s_waitcnt vmcnt(" #n ")" ::: "memory")
; #define BAR8 __builtin_amdgcn_s_barrier()
; #define G_XF (outp())
; #define G_SS ((float*)(wsp() + OFF_SS))
;     ...
;     STAGE8(SB8(0, 0), Bt, K, bcol, 0); STAGE8(SA8(0, 0), A, lda, brow, 0);
;     STAGE8(SB8(0, 1), Bt, K, bcol + 128, 0); STAGE8(SA8(0, 1), A, lda, brow + 128, 0);
;   }
;   if (wr == 1) BAR8;
;   WAIT_V8(4); BAR8;
;   STAGE8(SB8(1, 0), Bt, K, bcol, 1); STAGE8(SA8(1, 0), A, lda, brow, 1); STAGE8(SB8(1, 1), Bt, K, bcol + 128, 1);
; __global__ void __launch_bounds__(512, 2) mega(Params p) {
;     ...
;     for (int item = bid; item < 4 * 64; item += nb) {
;       const int nt = item >> 6, mt = item & 63;
;       e.ss = nullptr; e.xf = G_XF; e.xb = G_XB; e.ss_out = G_SS;
;       gemm_tile<EPI_RESID, 256, false>(G_OB, DM, wb + W_OUT, DM, mt * 256, nt * 256, e);
.LBB0_905:
	s_mov_b32 s0, 24
	s_mov_b32 s0, 25
	s_ashr_i32 s1, s0, 31
	s_lshl_b64 s[0:1], s[0:1], 3
	s_add_u32 s0, s70, s0
	s_addc_u32 s1, s71, s1
	v_readlane_b32 s6, v255, 60
	v_readlane_b32 s7, v255, 61
	s_nop 3
	s_mov_b32 s0, 25
	s_ashr_i32 s1, s0, 31
	s_lshl_b64 s[0:1], s[0:1], 3
	s_add_u32 s0, s70, s0
	s_addc_u32 s1, s71, s1
	s_mov_b32 s2, 25
	v_readlane_b32 s0, v255, 60
	v_readlane_b32 s1, v255, 61
	s_nop 3
	s_ashr_i32 s3, s2, 31
	s_lshl_b64 s[2:3], s[2:3], 3
	s_add_u32 s2, s70, s2
	s_addc_u32 s3, s71, s3
	v_mov_b32_e32 v3, v224
	v_readlane_b32 s2, v255, 60
	v_readlane_b32 s3, v255, 61
	s_nop 3
	v_mov_b32_e32 v18, 1
	v_bfe_i32 v1, v3, 27, 1
	s_waitcnt vmcnt(10)
	v_lshlrev_b32_e32 v150, 4, v3
	v_lshrrev_b32_e32 v1, 22, v1
	v_add_u32_e32 v1, v150, v1
	v_and_b32_e32 v1, 0xfffffc00, v1
	v_ashrrev_i32_e32 v0, 31, v3
	v_sub_u32_e32 v1, v150, v1
	v_lshrrev_b32_e32 v0, 26, v0
	v_lshrrev_b32_e32 v5, 4, v1
	v_add_u32_e32 v0, v3, v0
	v_bitop3_b32 v5, v5, v1, 32 bitop3:0x6c
	v_ashrrev_i32_e32 v1, 31, v1
	s_waitcnt lgkmcnt(0)
	s_add_u32 s29, s2, 0x6000000
	v_ashrrev_i32_e32 v0, 6, v0
	v_lshrrev_b32_e32 v1, 26, v1
	s_addc_u32 s33, s3, 0
	s_lshl_b32 s8, s24, 8
	v_lshlrev_b32_e32 v6, 3, v0
	v_add_u32_e32 v1, v5, v1
	s_and_b32 s25, s8, 0x3f00
	s_lshl_b32 s8, s24, 2
	v_and_b32_e32 v6, -16, v6
	v_ashrrev_i32_e32 v1, 6, v1
	s_and_b32 s8, s8, 0xffffff00
	v_add_u32_e32 v16, v1, v6
	v_mul_i32_i24_e32 v1, 64, v1
	s_ashr_i32 s9, s8, 31
	v_lshlrev_b32_e32 v0, 5, v0
	v_sub_u32_e32 v1, v5, v1
	s_waitcnt vmcnt(9)
	v_add_u32_e32 v152, 0x2000, v150
	s_lshl_b64 s[12:13], s[8:9], 11
	v_and_b32_e32 v0, 32, v0
	v_ashrrev_i16_sdwa v1, v18, sext(v1) dst_sel:DWORD dst_unused:UNUSED_PAD src0_sel:DWORD src1_sel:BYTE_0
	v_ashrrev_i32_e32 v5, 31, v152
	s_add_u32 s12, s14, s12
	v_add_u32_sdwa v0, v0, sext(v1) dst_sel:DWORD dst_unused:UNUSED_PAD src0_sel:DWORD src1_sel:WORD_0
	v_ashrrev_i32_e32 v17, 31, v16
	v_lshrrev_b32_e32 v5, 22, v5
	s_addc_u32 s13, s15, s13
	v_lshlrev_b64 v[6:7], 11, v[16:17]
	v_ashrrev_i32_e32 v1, 31, v0
	v_add_u32_e32 v5, v152, v5
	v_lshl_add_u64 v[10:11], s[12:13], 0, v[6:7]
	v_lshlrev_b64 v[8:9], 1, v[0:1]
	v_ashrrev_i32_e32 v5, 10, v5
	v_lshl_add_u64 v[14:15], v[10:11], 0, v[8:9]
	v_mul_i32_i24_e32 v10, 0x400, v5
	v_sub_u32_e32 v10, v152, v10
	v_lshrrev_b32_e32 v11, 4, v10
	v_bitop3_b32 v10, v11, v10, 32 bitop3:0x6c
	v_ashrrev_i32_e32 v12, 31, v10
	v_lshrrev_b32_e32 v12, 26, v12
	v_lshlrev_b32_e32 v11, 3, v5
	v_add_u32_e32 v12, v10, v12
	v_and_b32_e32 v11, -16, v11
	v_ashrrev_i32_e32 v13, 6, v12
	v_add_u32_e32 v24, v13, v11
	v_and_b32_e32 v11, 0xc0, v12
	v_lshlrev_b32_e32 v5, 5, v5
	v_sub_u32_e32 v10, v10, v11
	v_add_u32_e32 v151, 0x10000, v150
	v_and_b32_e32 v5, 32, v5
	v_ashrrev_i16_sdwa v10, v18, sext(v10) dst_sel:DWORD dst_unused:UNUSED_PAD src0_sel:DWORD src1_sel:BYTE_0
	v_ashrrev_i32_e32 v25, 31, v24
	v_readfirstlane_b32 s27, v151
	v_add_u32_sdwa v132, v5, sext(v10) dst_sel:DWORD dst_unused:UNUSED_PAD src0_sel:DWORD src1_sel:WORD_0
	v_lshlrev_b64 v[10:11], 11, v[24:25]
	s_waitcnt vmcnt(8)
	v_add_u32_e32 v157, 0x12000, v150
	v_mov_b32_e32 v4, v2
	s_mov_b32 m0, s27
	v_lshl_add_u64 v[18:19], s[12:13], 0, v[10:11]
	v_readfirstlane_b32 s12, v157
	global_load_lds_dwordx4 v[14:15], off
	v_ashrrev_i32_e32 v133, 31, v132
	s_mov_b32 m0, s12
	s_lshl_b32 s27, s25, 10
	s_lshl_b32 s12, s25, 11
	v_lshlrev_b64 v[12:13], 1, v[132:133]
	s_add_u32 s12, s29, s12
	v_lshl_add_u64 v[18:19], v[18:19], 0, v[12:13]
	s_addc_u32 s13, s33, 0
	v_readfirstlane_b32 s30, v150
	global_load_lds_dwordx4 v[18:19], off
	v_lshl_add_u64 v[20:21], s[12:13], 0, v[6:7]
	s_mov_b32 m0, s30
	s_or_b32 s30, s8, 0x80
	v_lshl_add_u64 v[20:21], v[20:21], 0, v[8:9]
	v_lshl_add_u64 v[22:23], s[12:13], 0, v[10:11]
	v_readfirstlane_b32 s12, v152
	s_ashr_i32 s31, s30, 31
	global_load_lds_dwordx4 v[20:21], off
	s_mov_b32 m0, s12
	s_lshl_b64 s[12:13], s[30:31], 11
	s_add_u32 s12, s14, s12
	s_addc_u32 s13, s15, s13
	v_add_u32_e32 v159, 0x14000, v150
	v_lshl_add_u64 v[22:23], v[22:23], 0, v[12:13]
	v_lshl_add_u64 v[26:27], s[12:13], 0, v[6:7]
	v_readfirstlane_b32 s31, v159
	v_add_u32_e32 v161, 0x16000, v150
	s_bitset1_b32 s27, 17
	global_load_lds_dwordx4 v[22:23], off
	v_lshl_add_u64 v[26:27], v[26:27], 0, v[8:9]
	s_mov_b32 m0, s31
	v_lshl_add_u64 v[28:29], s[12:13], 0, v[10:11]
	v_readfirstlane_b32 s12, v161
	s_lshl_b32 s27, s27, 1
	global_load_lds_dwordx4 v[26:27], off
	s_mov_b32 m0, s12
	s_add_u32 s12, s29, s27
	s_addc_u32 s13, s33, 0
	v_add_u32_e32 v162, 0x4000, v150
	v_lshl_add_u64 v[28:29], v[28:29], 0, v[12:13]
	v_lshl_add_u64 v[30:31], s[12:13], 0, v[6:7]
	v_readfirstlane_b32 s29, v162
	global_load_lds_dwordx4 v[28:29], off
	v_lshl_add_u64 v[30:31], v[30:31], 0, v[8:9]
	s_mov_b32 m0, s29
	v_add_u32_e32 v163, 0x6000, v150
	global_load_lds_dwordx4 v[30:31], off
	v_lshl_add_u64 v[30:31], s[12:13], 0, v[10:11]
	v_readfirstlane_b32 s12, v163
	v_lshl_add_u64 v[30:31], v[30:31], 0, v[12:13]
	s_mov_b32 m0, s12
	v_ashrrev_i32_e32 v5, 8, v3
	global_load_lds_dwordx4 v[30:31], off
	v_cmp_eq_u32_e32 vcc, 1, v5
	s_and_saveexec_b64 s[12:13], vcc
	s_cbranch_execz .LBB0_907
	s_barrier

; #define WAIT_V8(n) asm volatile("s_waitcnt vmcnt(" #n ")" ::: "memory")
; #define BAR8 __builtin_amdgcn_s_barrier()
; #define G_SSMEM ((float*)(wsp() + OFF_SSMEM))
;     ...
;     STAGE8(SB8(0, 0), Bt, K, bcol, 0); STAGE8(SA8(0, 0), A, lda, brow, 0);
;     STAGE8(SB8(0, 1), Bt, K, bcol + 128, 0); STAGE8(SA8(0, 1), A, lda, brow + 128, 0);
;   }
;   if (wr == 1) BAR8;
;   WAIT_V8(4); BAR8;
;   STAGE8(SB8(1, 0), Bt, K, bcol, 1); STAGE8(SA8(1, 0), A, lda, brow, 1); STAGE8(SB8(1, 1), Bt, K, bcol + 128, 1);
; __global__ void __launch_bounds__(512, 2) mega(Params p) {
;     ...
;         const int it = item - 128;
;         const int nt = it >> 3, mt = it & 7;
;         e.ss = G_SSMEM; e.nss = 1; e.inv_n = 1.f / 1024.f; e.out = G_MEMKV; e.ldo = 1024;
;         gemm_tile<EPI_PLAIN, 256, false>(G_MEMB, DM, wb + W_XKV, DM, mt * 256, nt * 256, e);
.LBB0_1001:
	s_lshr_b32 s27, s37, 8
	s_cmpk_gt_i32 s38, 0x7f
	s_mov_b64 s[0:1], -1
	s_cbranch_scc0 .LBB0_1011
	s_mov_b32 s0, 25
	s_ashr_i32 s1, s0, 31
	s_lshl_b64 s[0:1], s[0:1], 3
	s_add_u32 s0, s70, s0
	s_addc_u32 s1, s71, s1
	v_readlane_b32 s6, v255, 60
	v_readlane_b32 s7, v255, 61
	s_nop 3
	s_mov_b32 s0, 25
	s_ashr_i32 s1, s0, 31
	s_lshl_b64 s[0:1], s[0:1], 3
	s_add_u32 s0, s70, s0
	s_addc_u32 s1, s71, s1
	v_readlane_b32 s2, v255, 60
	v_readlane_b32 s3, v255, 61
	s_nop 3
	s_mov_b32 s0, 25
	s_ashr_i32 s1, s0, 31
	s_lshl_b64 s[0:1], s[0:1], 3
	s_add_u32 s0, s70, s0
	s_addc_u32 s1, s71, s1
	v_mov_b32_e32 v3, v224
	v_readlane_b32 s12, v255, 60
	v_readlane_b32 s13, v255, 61
	s_nop 3
	s_lshl_b32 s0, s38, 8
	v_bfe_i32 v1, v3, 27, 1
	s_waitcnt vmcnt(10)
	v_lshlrev_b32_e32 v150, 4, v3
	v_lshrrev_b32_e32 v1, 22, v1
	v_add_u32_e32 v1, v150, v1
	v_and_b32_e32 v1, 0xfffffc00, v1
	v_ashrrev_i32_e32 v0, 31, v3
	v_sub_u32_e32 v1, v150, v1
	v_lshrrev_b32_e32 v0, 26, v0
	v_lshrrev_b32_e32 v5, 4, v1
	v_add_u32_e32 v0, v3, v0
	v_bitop3_b32 v5, v5, v1, 32 bitop3:0x6c
	v_ashrrev_i32_e32 v1, 31, v1
	v_ashrrev_i32_e32 v0, 6, v0
	v_lshrrev_b32_e32 v1, 26, v1
	v_lshlrev_b32_e32 v6, 3, v0
	v_add_u32_e32 v1, v5, v1
	s_and_b32 s29, s0, 0x700
	s_lshl_b32 s0, s38, 5
	v_and_b32_e32 v6, -16, v6
	v_ashrrev_i32_e32 v1, 6, v1
	s_and_b32 s39, s0, 0x7fffff00
	v_add_u32_e32 v6, v1, v6
	v_mul_i32_i24_e32 v1, 64, v1
	s_add_i32 s0, s39, 0xfffff000
	v_lshlrev_b32_e32 v0, 5, v0
	v_sub_u32_e32 v1, v5, v1
	v_mov_b32_e32 v14, 1
	s_waitcnt vmcnt(9)
	v_add_u32_e32 v152, 0x2000, v150
	s_lshl_b32 s1, s0, 11
	v_and_b32_e32 v0, 32, v0
	v_ashrrev_i16_sdwa v1, v14, sext(v1) dst_sel:DWORD dst_unused:UNUSED_PAD src0_sel:DWORD src1_sel:BYTE_0
	v_ashrrev_i32_e32 v5, 31, v152
	s_add_u32 s14, s24, s1
	v_add_u32_sdwa v0, v0, sext(v1) dst_sel:DWORD dst_unused:UNUSED_PAD src0_sel:DWORD src1_sel:WORD_0
	v_ashrrev_i32_e32 v7, 31, v6
	v_lshrrev_b32_e32 v5, 22, v5
	s_addc_u32 s15, s25, 0
	v_lshlrev_b64 v[132:133], 11, v[6:7]
	v_ashrrev_i32_e32 v1, 31, v0
	v_add_u32_e32 v5, v152, v5
	v_lshl_add_u64 v[8:9], s[14:15], 0, v[132:133]
	v_lshlrev_b64 v[6:7], 1, v[0:1]
	v_ashrrev_i32_e32 v5, 10, v5
	v_lshl_add_u64 v[10:11], v[8:9], 0, v[6:7]
	v_mul_i32_i24_e32 v8, 0x400, v5
	v_sub_u32_e32 v8, v152, v8
	v_lshrrev_b32_e32 v9, 4, v8
	v_bitop3_b32 v9, v9, v8, 32 bitop3:0x6c
	v_ashrrev_i32_e32 v12, 31, v9
	v_add_u32_e32 v151, 0x10000, v150
	v_lshrrev_b32_e32 v12, 26, v12
	v_readfirstlane_b32 s1, v151
	v_add_u32_e32 v12, v9, v12
	s_waitcnt vmcnt(8)
	v_add_u32_e32 v157, 0x12000, v150
	v_mov_b32_e32 v4, v2
	s_mov_b32 m0, s1
	v_lshlrev_b32_e32 v8, 3, v5
	v_ashrrev_i32_e32 v13, 6, v12
	v_and_b32_e32 v12, 0xc0, v12
	v_readfirstlane_b32 s1, v157
	global_load_lds_dwordx4 v[10:11], off
	v_and_b32_e32 v8, -16, v8
	v_lshlrev_b32_e32 v5, 5, v5
	v_sub_u32_e32 v9, v9, v12
	s_mov_b32 m0, s1
	s_lshl_b32 s1, s29, 11
	v_add_u32_e32 v8, v13, v8
	v_and_b32_e32 v5, 32, v5
	v_ashrrev_i16_sdwa v9, v14, sext(v9) dst_sel:DWORD dst_unused:UNUSED_PAD src0_sel:DWORD src1_sel:BYTE_0
	s_waitcnt lgkmcnt(0)
	s_add_u32 s1, s12, s1
	v_add_u32_sdwa v134, v5, sext(v9) dst_sel:DWORD dst_unused:UNUSED_PAD src0_sel:DWORD src1_sel:WORD_0
	v_ashrrev_i32_e32 v9, 31, v8
	s_addc_u32 s40, s13, 0
	v_lshlrev_b64 v[136:137], 11, v[8:9]
	v_ashrrev_i32_e32 v135, 31, v134
	s_add_u32 s8, s1, 0xb800000
	v_lshl_add_u64 v[12:13], s[14:15], 0, v[136:137]
	v_lshlrev_b64 v[8:9], 1, v[134:135]
	s_addc_u32 s9, s40, 0
	v_lshl_add_u64 v[12:13], v[12:13], 0, v[8:9]
	v_lshl_add_u64 v[14:15], s[8:9], 0, v[132:133]
	v_readfirstlane_b32 s20, v150
	global_load_lds_dwordx4 v[12:13], off
	v_lshl_add_u64 v[16:17], v[14:15], 0, v[6:7]
	s_mov_b32 m0, s20
	v_readfirstlane_b32 s20, v152
	global_load_lds_dwordx4 v[16:17], off
	s_mov_b32 m0, s20
	s_add_u32 s20, s14, 0x40000
	v_lshl_add_u64 v[14:15], s[8:9], 0, v[136:137]
	s_addc_u32 s21, s15, 0
	v_add_u32_e32 v159, 0x14000, v150
	v_lshl_add_u64 v[14:15], v[14:15], 0, v[8:9]
	v_lshl_add_u64 v[18:19], s[20:21], 0, v[132:133]
	v_readfirstlane_b32 s41, v159
	global_load_lds_dwordx4 v[14:15], off
	v_lshl_add_u64 v[18:19], v[18:19], 0, v[6:7]
	s_mov_b32 m0, s41
	v_add_u32_e32 v160, 0x16000, v150
	global_load_lds_dwordx4 v[18:19], off
	v_lshl_add_u64 v[18:19], s[20:21], 0, v[136:137]
	v_readfirstlane_b32 s20, v160
	s_mov_b32 m0, s20
	s_add_u32 s20, s1, 0xb840000
	v_lshl_add_u64 v[18:19], v[18:19], 0, v[8:9]
	s_addc_u32 s21, s40, 0
	v_add_u32_e32 v162, 0x4000, v150
	global_load_lds_dwordx4 v[18:19], off
	v_lshl_add_u64 v[18:19], s[20:21], 0, v[132:133]
	v_readfirstlane_b32 s1, v162
	v_lshl_add_u64 v[18:19], v[18:19], 0, v[6:7]
	s_mov_b32 m0, s1
	v_add_u32_e32 v163, 0x6000, v150
	global_load_lds_dwordx4 v[18:19], off
	v_lshl_add_u64 v[18:19], s[20:21], 0, v[136:137]
	v_readfirstlane_b32 s1, v163
	v_lshl_add_u64 v[18:19], v[18:19], 0, v[8:9]
	s_mov_b32 m0, s1
	v_ashrrev_i32_e32 v5, 8, v3
	global_load_lds_dwordx4 v[18:19], off
	v_cmp_eq_u32_e32 vcc, 1, v5
	s_and_saveexec_b64 s[20:21], vcc
	s_cbranch_execz .LBB0_1004
	s_barrier

; #define WAIT_V8(n) asm volatile("s_waitcnt vmcnt(" #n ")" ::: "memory")
; #define BAR8 __builtin_amdgcn_s_barrier()
; #define G_SS ((float*)(wsp() + OFF_SS))
;     ...
;     STAGE8(SB8(0, 0), Bt, K, bcol, 0); STAGE8(SA8(0, 0), A, lda, brow, 0);
;     STAGE8(SB8(0, 1), Bt, K, bcol + 128, 0); STAGE8(SA8(0, 1), A, lda, brow + 128, 0);
;   }
;   if (wr == 1) BAR8;
;   WAIT_V8(4); BAR8;
;   STAGE8(SB8(1, 0), Bt, K, bcol, 1); STAGE8(SA8(1, 0), A, lda, brow, 1); STAGE8(SB8(1, 1), Bt, K, bcol + 128, 1);
; __global__ void __launch_bounds__(512, 2) mega(Params p) {
;     ...
;       if (item < 128) {
;         const int nt = item >> 6, mt = item & 63;
;         e.ss = G_SS; e.nss = 16; e.inv_n = 1.f / 1024.f; e.out = G_XQ; e.ldo = 512;
;         gemm_tile<EPI_PLAIN, 256, true>(G_XB, DM, wb + W_XQ, DM, mt * 256, nt * 256, e);
.LBB0_1011:
	s_and_b64 vcc, exec, s[0:1]
	s_cbranch_vccz .LBB0_1000
	s_mov_b32 s0, 25
	s_ashr_i32 s1, s0, 31
	s_lshl_b64 s[0:1], s[0:1], 3
	s_add_u32 s0, s70, s0
	s_addc_u32 s1, s71, s1
	v_readlane_b32 s6, v255, 60
	v_readlane_b32 s7, v255, 61
	s_nop 3
	s_mov_b32 s0, 25
	s_ashr_i32 s1, s0, 31
	s_lshl_b64 s[0:1], s[0:1], 3
	s_add_u32 s0, s70, s0
	s_addc_u32 s1, s71, s1
	v_readlane_b32 s2, v255, 60
	v_readlane_b32 s3, v255, 61
	s_nop 3
	s_mov_b32 s0, 25
	s_ashr_i32 s1, s0, 31
	s_lshl_b64 s[0:1], s[0:1], 3
	s_add_u32 s0, s70, s0
	s_addc_u32 s1, s71, s1
	v_mov_b32_e32 v3, v224
	v_readlane_b32 s12, v255, 60
	v_readlane_b32 s13, v255, 61
	s_nop 3
	s_lshl_b32 s0, s38, 8
	v_bfe_i32 v1, v3, 27, 1
	s_waitcnt vmcnt(10)
	v_lshlrev_b32_e32 v150, 4, v3
	v_lshrrev_b32_e32 v1, 22, v1
	v_add_u32_e32 v1, v150, v1
	v_and_b32_e32 v1, 0xfffffc00, v1
	v_ashrrev_i32_e32 v0, 31, v3
	v_sub_u32_e32 v1, v150, v1
	v_lshrrev_b32_e32 v0, 26, v0
	v_lshrrev_b32_e32 v5, 4, v1
	v_add_u32_e32 v0, v3, v0
	v_bitop3_b32 v5, v5, v1, 32 bitop3:0x6c
	v_ashrrev_i32_e32 v1, 31, v1
	v_ashrrev_i32_e32 v0, 6, v0
	v_lshrrev_b32_e32 v1, 26, v1
	v_lshlrev_b32_e32 v6, 3, v0
	v_add_u32_e32 v1, v5, v1
	s_and_b32 s20, s0, 0x3f00
	s_lshl_b32 s0, s38, 2
	v_and_b32_e32 v6, -16, v6
	v_ashrrev_i32_e32 v1, 6, v1
	s_and_b32 s0, s0, 0xffffff00
	v_add_u32_e32 v6, v1, v6
	v_mul_i32_i24_e32 v1, 64, v1
	s_ashr_i32 s1, s0, 31
	v_lshlrev_b32_e32 v0, 5, v0
	v_sub_u32_e32 v1, v5, v1
	v_mov_b32_e32 v14, 1
	s_waitcnt vmcnt(9)
	v_add_u32_e32 v152, 0x2000, v150
	s_lshl_b64 s[8:9], s[0:1], 11
	v_and_b32_e32 v0, 32, v0
	v_ashrrev_i16_sdwa v1, v14, sext(v1) dst_sel:DWORD dst_unused:UNUSED_PAD src0_sel:DWORD src1_sel:BYTE_0
	v_ashrrev_i32_e32 v5, 31, v152
	s_add_u32 s8, s30, s8
	v_add_u32_sdwa v0, v0, sext(v1) dst_sel:DWORD dst_unused:UNUSED_PAD src0_sel:DWORD src1_sel:WORD_0
	v_ashrrev_i32_e32 v7, 31, v6
	v_lshrrev_b32_e32 v5, 22, v5
	s_addc_u32 s9, s31, s9
	v_lshlrev_b64 v[132:133], 11, v[6:7]
	v_ashrrev_i32_e32 v1, 31, v0
	v_add_u32_e32 v5, v152, v5
	v_lshl_add_u64 v[8:9], s[8:9], 0, v[132:133]
	v_lshlrev_b64 v[6:7], 1, v[0:1]
	v_ashrrev_i32_e32 v5, 10, v5
	v_lshl_add_u64 v[10:11], v[8:9], 0, v[6:7]
	v_mul_i32_i24_e32 v8, 0x400, v5
	v_sub_u32_e32 v8, v152, v8
	v_lshrrev_b32_e32 v9, 4, v8
	v_bitop3_b32 v9, v9, v8, 32 bitop3:0x6c
	v_ashrrev_i32_e32 v12, 31, v9
	v_lshrrev_b32_e32 v12, 26, v12
	v_add_u32_e32 v12, v9, v12
	v_lshlrev_b32_e32 v8, 3, v5
	v_ashrrev_i32_e32 v13, 6, v12
	v_and_b32_e32 v12, 0xc0, v12
	v_and_b32_e32 v8, -16, v8
	v_lshlrev_b32_e32 v5, 5, v5
	v_sub_u32_e32 v9, v9, v12
	v_add_u32_e32 v8, v13, v8
	v_and_b32_e32 v5, 32, v5
	v_ashrrev_i16_sdwa v9, v14, sext(v9) dst_sel:DWORD dst_unused:UNUSED_PAD src0_sel:DWORD src1_sel:BYTE_0
	v_add_u32_e32 v151, 0x10000, v150
	v_add_u32_sdwa v134, v5, sext(v9) dst_sel:DWORD dst_unused:UNUSED_PAD src0_sel:DWORD src1_sel:WORD_0
	v_ashrrev_i32_e32 v9, 31, v8
	v_readfirstlane_b32 s14, v151
	v_lshlrev_b64 v[136:137], 11, v[8:9]
	s_waitcnt vmcnt(8)
	v_add_u32_e32 v157, 0x12000, v150
	v_mov_b32_e32 v4, v2
	s_mov_b32 m0, s14
	v_lshl_add_u64 v[12:13], s[8:9], 0, v[136:137]
	v_readfirstlane_b32 s8, v157
	global_load_lds_dwordx4 v[10:11], off
	s_mov_b32 m0, s8
	s_lshl_b32 s8, s20, 11
	v_ashrrev_i32_e32 v135, 31, v134
	s_waitcnt lgkmcnt(0)
	s_add_u32 s8, s12, s8
	v_lshlrev_b64 v[8:9], 1, v[134:135]
	s_addc_u32 s9, s13, 0
	v_lshl_add_u64 v[12:13], v[12:13], 0, v[8:9]
	v_lshl_add_u64 v[14:15], s[8:9], 0, v[132:133]
	v_readfirstlane_b32 s14, v150
	global_load_lds_dwordx4 v[12:13], off
	v_lshl_add_u64 v[14:15], v[14:15], 0, v[6:7]
	s_mov_b32 m0, s14
	v_readfirstlane_b32 s14, v152
	global_load_lds_dwordx4 v[14:15], off
	s_mov_b32 m0, s14
	s_or_b32 s14, s0, 0x80
	s_ashr_i32 s15, s14, 31
	s_lshl_b64 s[14:15], s[14:15], 11
	s_add_u32 s14, s30, s14
	v_lshl_add_u64 v[16:17], s[8:9], 0, v[136:137]
	s_addc_u32 s15, s31, s15
	v_add_u32_e32 v159, 0x14000, v150
	v_lshl_add_u64 v[16:17], v[16:17], 0, v[8:9]
	v_lshl_add_u64 v[18:19], s[14:15], 0, v[132:133]
	v_readfirstlane_b32 s21, v159
	v_add_u32_e32 v160, 0x16000, v150
	global_load_lds_dwordx4 v[16:17], off
	v_lshl_add_u64 v[18:19], v[18:19], 0, v[6:7]
	s_mov_b32 m0, s21
	v_lshl_add_u64 v[20:21], s[14:15], 0, v[136:137]
	v_readfirstlane_b32 s14, v160
	global_load_lds_dwordx4 v[18:19], off
	s_mov_b32 m0, s14
	s_add_u32 s14, s8, 0x40000
	s_addc_u32 s15, s9, 0
	v_add_u32_e32 v162, 0x4000, v150
	v_lshl_add_u64 v[20:21], v[20:21], 0, v[8:9]
	v_lshl_add_u64 v[22:23], s[14:15], 0, v[132:133]
	v_readfirstlane_b32 s21, v162
	global_load_lds_dwordx4 v[20:21], off
	v_lshl_add_u64 v[22:23], v[22:23], 0, v[6:7]
	s_mov_b32 m0, s21
	v_add_u32_e32 v163, 0x6000, v150
	global_load_lds_dwordx4 v[22:23], off
	v_lshl_add_u64 v[22:23], s[14:15], 0, v[136:137]
	v_readfirstlane_b32 s14, v163
	v_lshl_add_u64 v[22:23], v[22:23], 0, v[8:9]
	s_mov_b32 m0, s14
	v_ashrrev_i32_e32 v5, 8, v3
	global_load_lds_dwordx4 v[22:23], off
	v_cmp_eq_u32_e32 vcc, 1, v5
	s_and_saveexec_b64 s[14:15], vcc
	s_cbranch_execz .LBB0_1014
	s_barrier

; template <int DK, int DV, int MODE>
; DI void att_gload(const AttArgs& a, int tile, u32x4 (&kr)[(64 * (DK / 8) + NT - 1) / NT], u32x4 (&vr)[(64 * (DV / 8) + NT - 1) / NT]) {
;     ...
; #pragma unroll
;   for (int i = 0; i < NKL; ++i) {
;     const int id = min(t + NT * i, 64 * CK - 1);
;     const int row = id / CK, c = id % CK;
;     if constexpr (MODE == 3) {
;       const bf16_t* src = (c < 8) ? (a.k + (size_t)(kbase + row) * a.ldk + c * 8) : (a.k2 + (size_t)(kbase + row) * a.ldk2 + (c - 8) * 8);
;       kr[i] = *(const u32x4*)src;
;     } else {
;       kr[i] = *(const u32x4*)(a.k + (size_t)(kbase + row) * a.ldk + c * 8);
;     }
;   }
; #pragma unroll
;   for (int i = 0; i < NVL; ++i) {
;     const int id = t + NT * i;
;     const int row = id / CV, c = id % CV;
;     vr[i] = *(const u32x4*)(a.v + (size_t)(kbase + row) * a.ldv + c * 8);
;   }
; }
; template <int DK, int DV>
; DI void att_swrite(int buf, const u32x4 (&kr)[(64 * (DK / 8) + NT - 1) / NT], const u32x4 (&vr)[(64 * (DV / 8) + NT - 1) / NT]) {
;   constexpr int CK = DK / 8, CV = DV / 8;
;   constexpr int KST = DK * 2 + 16, VST = DV * 2 + 16;
;   constexpr int KBYTES = 64 * KST, VBYTES = 64 * VST, BUFB = KBYTES + VBYTES;
;   constexpr int NKL = (64 * CK + NT - 1) / NT, NVL = (64 * CV + NT - 1) / NT;
;   const int t = tid_opaque();
; #pragma unroll
;   for (int i = 0; i < NKL; ++i) {
;     const int id = t + NT * i;
;     const int row = id / CK, c = id % CK;
;     if (id < 64 * CK) *(u32x4*)(smem + buf * BUFB + row * KST + c * 16) = kr[i];
;   }
; #pragma unroll
;   for (int i = 0; i < NVL; ++i) {
;     const int id = t + NT * i;
;     const int row = id / CV, c = id % CV;
;     *(u32x4*)(smem + buf * BUFB + KBYTES + row * VST + c * 16) = vr[i];
; __global__ void __launch_bounds__(512, 2) mega(Params p) {
;     ...
;       const int pl = item & 7, rest = item >> 3;
;       const int qt = rest & 7, pg = rest >> 3;
;       const int pair = pg * 8 + pl;
;       const int b = pair >> 2, hd = pair & 3;
;       AttArgs a{};
;       a.q = G_XQ + (size_t)b * SEQ * 512 + hd * 128; a.ldq = 512;
;       a.k = G_MEMKV + (size_t)b * 256 * 1024 + hd * 128; a.ldk = 1024;
;       a.v = G_MEMKV + (size_t)b * 256 * 1024 + 512 + hd * 128; a.ldv = 1024;
;       a.o = G_XO + (size_t)b * SEQ * 512 + hd * 128; a.ldo = 512;
;       a.scale = 0.08838834764831845f;
;       attn_item<128, 128, 0, 1>(a, qt * 256, 0, 4);
.LBB0_1077:
	s_ashr_i32 s1, s14, 3
	s_and_b32 s0, s14, 4
	s_and_b32 s1, s1, -8
	s_or_b32 s0, s1, s0
	s_ashr_i32 s4, s0, 2
	s_mov_b32 s0, 25
	s_ashr_i32 s1, s0, 31
	s_lshl_b64 s[0:1], s[0:1], 3
	s_add_u32 s0, s70, s0
	s_addc_u32 s1, s71, s1
	v_readlane_b32 s0, v255, 60
	v_readlane_b32 s1, v255, 61
	s_nop 3
	s_ashr_i32 s5, s4, 31
	s_lshl_b64 s[2:3], s[4:5], 21
	v_mov_b32_e32 v3, v224
	v_mov_b32_e32 v163, v2
	s_waitcnt lgkmcnt(0)
	s_add_u32 s0, s0, s2
	s_addc_u32 s1, s1, s3
	s_lshl_b32 s2, s14, 7
	s_and_b32 s2, s2, 0x180
	s_lshl_b32 s15, s2, 1
	s_add_u32 s8, s0, s15
	s_mov_b32 s0, 25
	s_addc_u32 s9, s1, 0
	s_ashr_i32 s1, s0, 31
	s_lshl_b64 s[0:1], s[0:1], 3
	s_add_u32 s0, s70, s0
	s_addc_u32 s1, s71, s1
	v_readlane_b32 s0, v255, 60
	v_readlane_b32 s1, v255, 61
	s_nop 3
	s_lshl_b64 s[6:7], s[4:5], 19
	v_mov_b32_e32 v10, v224
	v_mov_b32_e32 v22, v224
	s_waitcnt lgkmcnt(0)
	s_add_u32 s0, s0, s6
	s_addc_u32 s1, s1, s7
	s_add_u32 s0, s0, s15
	s_addc_u32 s1, s1, 0
	s_add_u32 s2, s0, 0xbc00000
	s_mov_b32 s0, 25
	s_addc_u32 s3, s1, 0
	s_ashr_i32 s1, s0, 31
	s_lshl_b64 s[0:1], s[0:1], 3
	s_add_u32 s0, s70, s0
	s_addc_u32 s1, s71, s1
	v_readlane_b32 s0, v255, 60
	v_readlane_b32 s1, v255, 61
	s_nop 3
	s_waitcnt lgkmcnt(0)
	s_add_u32 s0, s0, s6
	s_addc_u32 s1, s1, s7
	s_add_u32 s0, s0, s15
	s_addc_u32 s1, s1, 0
	s_add_u32 s6, s0, 0xbc00400
	s_mov_b32 s0, 25
	s_addc_u32 s7, s1, 0
	s_ashr_i32 s1, s0, 31
	s_lshl_b64 s[0:1], s[0:1], 3
	s_add_u32 s0, s70, s0
	s_addc_u32 s1, s71, s1
	s_lshl_b32 s12, s14, 5
	s_and_b32 s12, s12, 0x700
	v_ashrrev_i32_e32 v0, 1, v3
	v_and_b32_e32 v0, 0xffffffe0, v0
	v_and_b32_e32 v20, 31, v3
	v_add_u32_e32 v0, s12, v0
	v_or_b32_e32 v0, v0, v20
	v_ashrrev_i32_e32 v1, 31, v0
	v_bfe_u32 v21, v3, 5, 1
	v_lshlrev_b64 v[4:5], 10, v[0:1]
	v_lshl_add_u64 v[4:5], s[8:9], 0, v[4:5]
	v_lshlrev_b32_e32 v162, 4, v21
	v_lshl_add_u64 v[4:5], v[4:5], 0, v[162:163]
	s_mov_b64 s[8:9], 0x2000000
	v_lshl_add_u64 v[6:7], v[4:5], 0, s[8:9]
	s_brev_b32 s8, 64
	v_add_co_u32_e32 v4, vcc, s8, v4
	s_movk_i32 s8, 0x400
	s_nop 0
	v_addc_co_u32_e32 v5, vcc, 0, v5, vcc
	global_load_dwordx4 v[136:139], v[6:7], off offset:32
	global_load_dwordx4 v[132:135], v[6:7], off offset:64
	global_load_dwordx4 v[128:131], v[6:7], off offset:96
	global_load_dwordx4 v[124:127], v[6:7], off offset:128
	global_load_dwordx4 v[120:123], v[6:7], off offset:160
	global_load_dwordx4 v[116:119], v[6:7], off offset:192
	global_load_dwordx4 v[140:143], v[4:5], off
	global_load_dwordx4 v[112:115], v[6:7], off offset:224
	s_nop 0
	v_min_i32_e32 v5, 0x3ff, v10
	v_ashrrev_i32_e32 v4, 31, v5
	v_lshrrev_b32_e32 v4, 28, v4
	v_add_u32_e32 v6, v5, v4
	v_ashrrev_i32_e32 v4, 4, v6
	v_and_b32_e32 v6, 0x1ffffff0, v6
	v_sub_u32_e32 v6, v5, v6
	v_ashrrev_i32_e32 v5, 31, v4
	v_lshlrev_b64 v[4:5], 11, v[4:5]
	v_lshlrev_b32_e32 v6, 3, v6
	v_lshl_add_u64 v[4:5], s[2:3], 0, v[4:5]
	v_ashrrev_i32_e32 v7, 31, v6
	v_add_u32_e32 v12, 0x200, v10
	v_lshl_add_u64 v[4:5], v[6:7], 1, v[4:5]
	v_min_i32_e32 v7, 0x3ff, v12
	v_ashrrev_i32_e32 v6, 31, v7
	v_lshrrev_b32_e32 v6, 28, v6
	v_add_u32_e32 v8, v7, v6
	v_ashrrev_i32_e32 v6, 4, v8
	v_and_b32_e32 v8, 0x1ffffff0, v8
	v_sub_u32_e32 v8, v7, v8
	v_ashrrev_i32_e32 v7, 31, v6
	v_lshlrev_b64 v[6:7], 11, v[6:7]
	v_lshlrev_b32_e32 v8, 3, v8
	v_lshl_add_u64 v[6:7], s[2:3], 0, v[6:7]
	v_ashrrev_i32_e32 v9, 31, v8
	v_lshl_add_u64 v[6:7], v[8:9], 1, v[6:7]
	v_ashrrev_i32_e32 v8, 31, v10
	v_lshrrev_b32_e32 v8, 28, v8
	v_add_u32_e32 v9, v10, v8
	v_ashrrev_i32_e32 v8, 4, v9
	v_and_b32_e32 v9, 0x1ffffff0, v9
	v_sub_u32_e32 v10, v10, v9
	v_ashrrev_i32_e32 v9, 31, v8
	v_lshlrev_b64 v[8:9], 11, v[8:9]
	v_lshlrev_b32_e32 v10, 3, v10
	v_lshl_add_u64 v[8:9], s[6:7], 0, v[8:9]
	v_ashrrev_i32_e32 v11, 31, v10
	v_lshl_add_u64 v[8:9], v[10:11], 1, v[8:9]
	v_ashrrev_i32_e32 v10, 31, v12
	v_lshrrev_b32_e32 v10, 28, v10
	v_add_u32_e32 v11, v12, v10
	v_ashrrev_i32_e32 v10, 4, v11
	v_and_b32_e32 v11, 0x1ffffff0, v11
	v_sub_u32_e32 v12, v12, v11
	v_ashrrev_i32_e32 v11, 31, v10
	v_lshlrev_b64 v[10:11], 11, v[10:11]
	v_lshlrev_b32_e32 v12, 3, v12
	v_lshl_add_u64 v[10:11], s[6:7], 0, v[10:11]
	v_ashrrev_i32_e32 v13, 31, v12
	v_lshl_add_u64 v[10:11], v[12:13], 1, v[10:11]
	global_load_dwordx4 v[16:19], v[4:5], off
	s_nop 0
	global_load_dwordx4 v[4:7], v[6:7], off
	s_nop 0
	global_load_dwordx4 v[12:15], v[8:9], off
	s_nop 0
	global_load_dwordx4 v[8:11], v[10:11], off
	s_nop 0
	v_ashrrev_i32_e32 v23, 31, v22
	v_cmp_gt_i32_e32 vcc, s8, v22
	v_lshrrev_b32_e32 v23, 28, v23
	s_and_saveexec_b64 s[8:9], vcc
	s_cbranch_execz .LBB0_1079
	v_add_u32_e32 v24, v22, v23
	v_and_b32_e32 v25, 0xffffff0, v24
	v_lshrrev_b32_e32 v24, 4, v24
	s_movk_i32 s12, 0x110
	v_sub_u32_e32 v25, v22, v25
	v_mul_lo_u32 v24, v24, s12
	v_lshl_add_u32 v24, v25, 4, v24
	s_waitcnt vmcnt(3)
	ds_write_b128 v24, v[16:19]

; #define WAIT_V8(n) asm volatile("s_waitcnt vmcnt(" #n ")" ::: "memory")
; #define BAR8 __builtin_amdgcn_s_barrier()
; #define G_XF (outp())
; #define G_SS ((float*)(wsp() + OFF_SS))
;     ...
;     STAGE8(SB8(0, 0), Bt, K, bcol, 0); STAGE8(SA8(0, 0), A, lda, brow, 0);
;     STAGE8(SB8(0, 1), Bt, K, bcol + 128, 0); STAGE8(SA8(0, 1), A, lda, brow + 128, 0);
;   }
;   if (wr == 1) BAR8;
;   WAIT_V8(4); BAR8;
;   STAGE8(SB8(1, 0), Bt, K, bcol, 1); STAGE8(SA8(1, 0), A, lda, brow, 1); STAGE8(SB8(1, 1), Bt, K, bcol + 128, 1);
; __global__ void __launch_bounds__(512, 2) mega(Params p) {
;     ...
;     for (int item = bid; item < 4 * 64; item += nb) {
;       const int nt = item >> 6, mt = item & 63;
;       e.ss = nullptr; e.xf = G_XF; e.xb = G_XB; e.ss_out = G_SS;
;       gemm_tile<EPI_RESID, 256, false>(G_XO, 512, wb + W_XO, 512, mt * 256, nt * 256, e);
.LBB0_1149:
	s_mov_b32 s0, 24
	s_mov_b32 s0, 25
	s_ashr_i32 s1, s0, 31
	s_lshl_b64 s[0:1], s[0:1], 3
	s_add_u32 s0, s70, s0
	s_addc_u32 s1, s71, s1
	v_readlane_b32 s6, v255, 60
	v_readlane_b32 s7, v255, 61
	s_nop 3
	s_mov_b32 s0, 25
	s_ashr_i32 s1, s0, 31
	s_lshl_b64 s[0:1], s[0:1], 3
	s_add_u32 s0, s70, s0
	s_addc_u32 s1, s71, s1
	s_mov_b32 s2, 25
	v_readlane_b32 s0, v255, 60
	v_readlane_b32 s1, v255, 61
	s_nop 3
	s_ashr_i32 s3, s2, 31
	s_lshl_b64 s[2:3], s[2:3], 3
	s_add_u32 s2, s70, s2
	s_addc_u32 s3, s71, s3
	v_mov_b32_e32 v3, v224
	v_readlane_b32 s2, v255, 60
	v_readlane_b32 s3, v255, 61
	s_nop 3
	v_mov_b32_e32 v18, 1
	v_bfe_i32 v1, v3, 27, 1
	s_waitcnt vmcnt(10)
	v_lshlrev_b32_e32 v150, 4, v3
	v_lshrrev_b32_e32 v1, 22, v1
	v_add_u32_e32 v1, v150, v1
	v_and_b32_e32 v1, 0xfffffc00, v1
	v_ashrrev_i32_e32 v0, 31, v3
	v_sub_u32_e32 v1, v150, v1
	v_lshrrev_b32_e32 v0, 26, v0
	v_lshrrev_b32_e32 v5, 4, v1
	v_add_u32_e32 v0, v3, v0
	v_bitop3_b32 v5, v5, v1, 32 bitop3:0x6c
	v_ashrrev_i32_e32 v1, 31, v1
	s_waitcnt lgkmcnt(0)
	s_add_u32 s29, s2, 0x3000000
	v_ashrrev_i32_e32 v0, 6, v0
	v_lshrrev_b32_e32 v1, 26, v1
	s_addc_u32 s33, s3, 0
	s_lshl_b32 s8, s24, 8
	v_lshlrev_b32_e32 v6, 3, v0
	v_add_u32_e32 v1, v5, v1
	s_and_b32 s25, s8, 0x3f00
	s_lshl_b32 s8, s24, 2
	v_and_b32_e32 v6, -16, v6
	v_ashrrev_i32_e32 v1, 6, v1
	s_and_b32 s8, s8, 0xffffff00
	v_add_u32_e32 v16, v1, v6
	v_mul_i32_i24_e32 v1, 64, v1
	s_ashr_i32 s9, s8, 31
	v_lshlrev_b32_e32 v0, 5, v0
	v_sub_u32_e32 v1, v5, v1
	s_waitcnt vmcnt(9)
	v_add_u32_e32 v152, 0x2000, v150
	s_lshl_b64 s[12:13], s[8:9], 10
	v_and_b32_e32 v0, 32, v0
	v_ashrrev_i16_sdwa v1, v18, sext(v1) dst_sel:DWORD dst_unused:UNUSED_PAD src0_sel:DWORD src1_sel:BYTE_0
	v_ashrrev_i32_e32 v5, 31, v152
	s_add_u32 s12, s14, s12
	v_add_u32_sdwa v0, v0, sext(v1) dst_sel:DWORD dst_unused:UNUSED_PAD src0_sel:DWORD src1_sel:WORD_0
	v_ashrrev_i32_e32 v17, 31, v16
	v_lshrrev_b32_e32 v5, 22, v5
	s_addc_u32 s13, s15, s13
	v_lshlrev_b64 v[6:7], 10, v[16:17]
	v_ashrrev_i32_e32 v1, 31, v0
	v_add_u32_e32 v5, v152, v5
	v_lshl_add_u64 v[10:11], s[12:13], 0, v[6:7]
	v_lshlrev_b64 v[8:9], 1, v[0:1]
	v_ashrrev_i32_e32 v5, 10, v5
	v_lshl_add_u64 v[14:15], v[10:11], 0, v[8:9]
	v_mul_i32_i24_e32 v10, 0x400, v5
	v_sub_u32_e32 v10, v152, v10
	v_lshrrev_b32_e32 v11, 4, v10
	v_bitop3_b32 v10, v11, v10, 32 bitop3:0x6c
	v_ashrrev_i32_e32 v12, 31, v10
	v_lshrrev_b32_e32 v12, 26, v12
	v_lshlrev_b32_e32 v11, 3, v5
	v_add_u32_e32 v12, v10, v12
	v_and_b32_e32 v11, -16, v11
	v_ashrrev_i32_e32 v13, 6, v12
	v_add_u32_e32 v24, v13, v11
	v_and_b32_e32 v11, 0xc0, v12
	v_lshlrev_b32_e32 v5, 5, v5
	v_sub_u32_e32 v10, v10, v11
	v_add_u32_e32 v151, 0x10000, v150
	v_and_b32_e32 v5, 32, v5
	v_ashrrev_i16_sdwa v10, v18, sext(v10) dst_sel:DWORD dst_unused:UNUSED_PAD src0_sel:DWORD src1_sel:BYTE_0
	v_ashrrev_i32_e32 v25, 31, v24
	v_readfirstlane_b32 s27, v151
	v_add_u32_sdwa v132, v5, sext(v10) dst_sel:DWORD dst_unused:UNUSED_PAD src0_sel:DWORD src1_sel:WORD_0
	v_lshlrev_b64 v[10:11], 10, v[24:25]
	s_waitcnt vmcnt(8)
	v_add_u32_e32 v157, 0x12000, v150
	v_mov_b32_e32 v4, v2
	s_mov_b32 m0, s27
	v_lshl_add_u64 v[18:19], s[12:13], 0, v[10:11]
	v_readfirstlane_b32 s12, v157
	global_load_lds_dwordx4 v[14:15], off
	v_ashrrev_i32_e32 v133, 31, v132
	s_mov_b32 m0, s12
	s_lshl_b32 s27, s25, 9
	s_lshl_b32 s12, s25, 10
	v_lshlrev_b64 v[12:13], 1, v[132:133]
	s_add_u32 s12, s29, s12
	v_lshl_add_u64 v[18:19], v[18:19], 0, v[12:13]
	s_addc_u32 s13, s33, 0
	v_readfirstlane_b32 s30, v150
	global_load_lds_dwordx4 v[18:19], off
	v_lshl_add_u64 v[20:21], s[12:13], 0, v[6:7]
	s_mov_b32 m0, s30
	s_or_b32 s30, s8, 0x80
	v_lshl_add_u64 v[20:21], v[20:21], 0, v[8:9]
	v_lshl_add_u64 v[22:23], s[12:13], 0, v[10:11]
	v_readfirstlane_b32 s12, v152
	s_ashr_i32 s31, s30, 31
	global_load_lds_dwordx4 v[20:21], off
	s_mov_b32 m0, s12
	s_lshl_b64 s[12:13], s[30:31], 10
	s_add_u32 s12, s14, s12
	s_addc_u32 s13, s15, s13
	v_add_u32_e32 v159, 0x14000, v150
	v_lshl_add_u64 v[22:23], v[22:23], 0, v[12:13]
	v_lshl_add_u64 v[26:27], s[12:13], 0, v[6:7]
	v_readfirstlane_b32 s31, v159
	v_add_u32_e32 v161, 0x16000, v150
	s_bitset1_b32 s27, 16
	global_load_lds_dwordx4 v[22:23], off
	v_lshl_add_u64 v[26:27], v[26:27], 0, v[8:9]
	s_mov_b32 m0, s31
	v_lshl_add_u64 v[28:29], s[12:13], 0, v[10:11]
	v_readfirstlane_b32 s12, v161
	s_lshl_b32 s27, s27, 1
	global_load_lds_dwordx4 v[26:27], off
	s_mov_b32 m0, s12
	s_add_u32 s12, s29, s27
	s_addc_u32 s13, s33, 0
	v_add_u32_e32 v162, 0x4000, v150
	v_lshl_add_u64 v[28:29], v[28:29], 0, v[12:13]
	v_lshl_add_u64 v[30:31], s[12:13], 0, v[6:7]
	v_readfirstlane_b32 s29, v162
	global_load_lds_dwordx4 v[28:29], off
	v_lshl_add_u64 v[30:31], v[30:31], 0, v[8:9]
	s_mov_b32 m0, s29
	v_add_u32_e32 v163, 0x6000, v150
	global_load_lds_dwordx4 v[30:31], off
	v_lshl_add_u64 v[30:31], s[12:13], 0, v[10:11]
	v_readfirstlane_b32 s12, v163
	v_lshl_add_u64 v[30:31], v[30:31], 0, v[12:13]
	s_mov_b32 m0, s12
	v_ashrrev_i32_e32 v5, 8, v3
	global_load_lds_dwordx4 v[30:31], off
	v_cmp_eq_u32_e32 vcc, 1, v5
	s_and_saveexec_b64 s[12:13], vcc
	s_cbranch_execz .LBB0_1151
	s_barrier

; #define WAIT_V0() asm volatile("s_waitcnt vmcnt(0)" ::: "memory")
; #define G_SS ((float*)(wsp() + OFF_SS))
; template <int EPI, int BN, bool F16>
; DI void gemm_tile(const bf16_t* __restrict__ A, int lda, const bf16_t* __restrict__ W, int K, int m0, int n0, const Ep& e) {
;     ...
;   f32x16 acc[MI][2];
; #pragma unroll
;   for (int i = 0; i < MI; ++i)
; #pragma unroll
;     for (int j = 0; j < 2; ++j)
; #pragma unroll
;       for (int k = 0; k < 16; ++k) acc[i][j][k] = 0.f;
;   const int grow = w * 8 + (l >> 3);
;   const int gch = (l & 7) ^ ((grow >> 1) & 7);
;   const bf16_t* ap = A + (size_t)(m0 + grow) * lda + gch * 8;
;   const bf16_t* wp = W + (size_t)(n0 + grow) * K + gch * 8;
;   unsigned char* lbase = smem + w * 1024;
;   const int sw = (r >> 1) & 7;
;   const unsigned char* ab = smem + (wm * (MI * 32) + r) * 128;
;   const unsigned char* bb = smem + 32768 + (wn * 64 + r) * 128;
;   const int nk = K >> 6;
;     ...
;   G_STAGE(0, 0)
;   WAIT_V0();
;   __syncthreads();
; __global__ void __launch_bounds__(512, 2) mega(Params p) {
;     ...
;     for (int item = bid; item < 20 * 64 + 4 * 64; item += nb) {
;       e.ss = G_SS; e.nss = 16; e.inv_n = 1.f / 1024.f; e.out = G_ACT; e.ldo = 2816;
;       if (item < 1280) {
;         const int nt = item >> 6, mt = item & 63;
;         const int nxt = item + nb;
;         const bool chain = nxt < 1280;
;         gemm_tile256<EPI_GU, true>(G_XB, DM, wb + W_GU, DM, mt * 256, nt * 256, e, pre7, chain ? (nxt & 63) * 256 : -1, (nxt >> 6) * 256);
;         pre7 = chain;
;       } else {
;         const int it = item - 1280;
;         const int nt = it >> 6, mt = it & 63;
;         gemm_tile<EPI_GU, 128, true>(G_XB, DM, wb + W_GU, DM, mt * 256, 5120 + nt * 128, e);
.LBB0_1245:
	s_mov_b32 s0, 25
	s_ashr_i32 s1, s0, 31
	s_lshr_b32 s12, s24, 8
	s_lshl_b64 s[0:1], s[0:1], 3
	s_add_u32 s0, s70, s0
	s_addc_u32 s1, s71, s1
	v_readlane_b32 s0, v255, 60
	v_readlane_b32 s1, v255, 61
	s_nop 3
	s_mov_b32 s2, 25
	s_waitcnt lgkmcnt(0)
	s_add_u32 s38, s0, 0xf640000
	s_addc_u32 s39, s1, 0
	s_ashr_i32 s3, s2, 31
	s_lshl_b64 s[0:1], s[2:3], 3
	s_add_u32 s0, s70, s0
	s_addc_u32 s1, s71, s1
	s_load_dwordx2 s[0:1], s[0:1], 0x0
	s_waitcnt lgkmcnt(0)
	s_add_u32 s30, s0, 0x2000000
	s_addc_u32 s31, s1, 0
	s_cmpk_gt_i32 s25, 0x4ff
	s_mov_b64 s[0:1], -1
	s_cbranch_scc0 .LBB0_1253
	s_mov_b32 s0, 25
	s_ashr_i32 s1, s0, 31
	s_and_b32 s27, s12, 63
	s_and_b32 s29, s21, 0x7fffff80
	s_lshl_b64 s[0:1], s[0:1], 3
	s_add_u32 s0, s70, s0
	s_addc_u32 s1, s71, s1
	v_readlane_b32 s2, v255, 60
	v_readlane_b32 s3, v255, 61
	s_nop 3
	s_lshl_b32 s0, s25, 8
	v_mov_b32_e32 v3, v224
	s_and_b32 s13, s0, 0x3f00
	s_lshl_b32 s0, s25, 1
	s_and_b32 s0, s0, 0x7fffff80
	v_ashrrev_i32_e32 v8, 6, v3
	v_lshlrev_b32_e32 v9, 3, v8
	v_bfe_u32 v10, v3, 3, 3
	s_addk_i32 s0, 0xa00
	v_or_b32_e32 v6, v9, v10
	v_lshrrev_b32_e32 v11, 1, v6
	v_add_u32_e32 v0, s13, v6
	v_add_u32_e32 v6, s0, v6
	v_xor_b32_e32 v4, v11, v3
	v_ashrrev_i32_e32 v1, 31, v0
	v_ashrrev_i32_e32 v7, 31, v6
	v_lshlrev_b64 v[0:1], 11, v[0:1]
	v_lshlrev_b32_e32 v4, 4, v4
	v_lshlrev_b64 v[6:7], 11, v[6:7]
	s_waitcnt lgkmcnt(0)
	v_lshl_add_u64 v[0:1], s[2:3], 0, v[0:1]
	v_and_b32_e32 v4, 0x70, v4
	v_mov_b32_e32 v5, v2
	v_lshl_add_u64 v[6:7], s[4:5], 0, v[6:7]
	v_lshl_add_u64 v[0:1], v[0:1], 0, v[4:5]
	v_lshl_add_u64 v[4:5], v[6:7], 0, v[4:5]
	v_lshlrev_b32_e32 v79, 10, v8
	v_ashrrev_i32_e32 v6, 1, v3
	v_and_b32_e32 v76, 31, v3
	v_and_b32_e32 v77, 0xffffffc0, v6
	v_add_u32_e32 v82, 0x8000, v79
	v_readfirstlane_b32 s1, v79
	v_or_b32_e32 v6, v77, v76
	s_mov_b32 m0, s1
	v_readfirstlane_b32 s1, v82
	v_add_u32_e32 v83, 0x2000, v79
	v_lshlrev_b32_e32 v80, 7, v6
	v_lshlrev_b32_e32 v6, 7, v3
	global_load_lds_dwordx4 v[0:1], off
	s_mov_b32 m0, s1
	s_mov_b64 s[14:15], 0x20000
	v_readfirstlane_b32 s1, v83
	v_add_u32_e32 v84, 0xa000, v79
	v_and_b32_e32 v81, 0x2f80, v6
	global_load_lds_dwordx4 v[4:5], off
	v_lshl_add_u64 v[6:7], v[0:1], 0, s[14:15]
	s_mov_b32 m0, s1
	v_readfirstlane_b32 s1, v84
	v_add_u32_e32 v85, 0x4000, v79
	global_load_lds_dwordx4 v[6:7], off
	v_lshl_add_u64 v[4:5], v[4:5], 0, s[14:15]
	s_mov_b32 m0, s1
	s_mov_b64 s[14:15], 0x40000
	v_readfirstlane_b32 s1, v85
	v_add_u32_e32 v86, 0x6000, v79
	global_load_lds_dwordx4 v[4:5], off
	v_lshl_add_u64 v[4:5], v[0:1], 0, s[14:15]
	s_mov_b32 m0, s1
	s_mov_b64 s[14:15], 0x60000
	v_readfirstlane_b32 s1, v86
	global_load_lds_dwordx4 v[4:5], off
	v_lshl_add_u64 v[0:1], v[0:1], 0, s[14:15]
	s_mov_b32 m0, s1
	v_lshl_or_b32 v4, s27, 8, v10
	global_load_lds_dwordx4 v[0:1], off
	v_add_u32_e32 v4, v4, v9
	v_ashrrev_i32_e32 v5, 31, v4
	v_lshlrev_b64 v[4:5], 11, v[4:5]
	v_lshrrev_b32_e32 v8, 1, v3
	v_bfe_u32 v78, v3, 5, 1
	v_lshl_add_u64 v[68:69], s[2:3], 0, v[4:5]
	v_or_b32_e32 v4, s29, v10
	s_movk_i32 s1, 0xa00
	v_bfe_u32 v0, v3, 1, 3
	v_bitop3_b32 v1, v78, v8, 7 bitop3:0x78
	v_add3_u32 v4, v4, v9, s1
	v_lshlrev_b32_e32 v89, 4, v1
	v_bitop3_b32 v1, v78, v0, 2 bitop3:0x36
	v_ashrrev_i32_e32 v5, 31, v4
	s_waitcnt vmcnt(0)
	v_lshlrev_b32_e32 v90, 4, v1
	v_bitop3_b32 v1, v78, v0, 4 bitop3:0x36
	v_bitop3_b32 v0, v78, v0, 6 bitop3:0x36
	v_lshlrev_b64 v[4:5], 11, v[4:5]
	v_lshlrev_b32_e32 v92, 4, v0
	v_bitop3_b32 v0, v11, 7, v3 bitop3:0x48
	v_lshl_add_u64 v[70:71], s[6:7], 0, v[4:5]
	v_mov_b32_e32 v4, 0
	v_add_u32_e32 v87, 0x10000, v79
	v_add_u32_e32 v88, 0x18000, v79
	v_lshlrev_b32_e32 v91, 4, v1
	v_add_u32_e32 v93, 0x10000, v80
	v_or_b32_e32 v94, 0x18000, v81
	v_add_u32_e32 v95, 0x12000, v79
	v_add_u32_e32 v96, 0x1a000, v79
	v_add_u32_e32 v97, 0x14000, v79
	v_add_u32_e32 v98, 0x16000, v79
	v_lshlrev_b32_e32 v0, 4, v0
	v_mov_b32_e32 v1, v2
	s_mov_b32 s1, 0
	v_mov_b32_e32 v5, v4
	v_mov_b64_e32 v[6:7], v[4:5]
	v_mov_b64_e32 v[8:9], v[4:5]
	v_mov_b64_e32 v[10:11], v[4:5]
	v_mov_b64_e32 v[12:13], v[4:5]
	v_mov_b64_e32 v[14:15], v[4:5]
	v_mov_b64_e32 v[16:17], v[4:5]
	v_mov_b64_e32 v[18:19], v[4:5]
	v_mov_b64_e32 v[20:21], v[4:5]
	v_mov_b64_e32 v[22:23], v[4:5]
	v_mov_b64_e32 v[24:25], v[4:5]
	v_mov_b64_e32 v[26:27], v[4:5]
	v_mov_b64_e32 v[28:29], v[4:5]
	v_mov_b64_e32 v[30:31], v[4:5]
	v_mov_b64_e32 v[32:33], v[4:5]
	v_mov_b64_e32 v[34:35], v[4:5]
	v_mov_b64_e32 v[36:37], v[4:5]
	v_mov_b64_e32 v[38:39], v[4:5]
	v_mov_b64_e32 v[40:41], v[4:5]
	v_mov_b64_e32 v[42:43], v[4:5]
	v_mov_b64_e32 v[44:45], v[4:5]
	v_mov_b64_e32 v[46:47], v[4:5]
	v_mov_b64_e32 v[48:49], v[4:5]
	v_mov_b64_e32 v[50:51], v[4:5]
	v_mov_b64_e32 v[52:53], v[4:5]
	v_mov_b64_e32 v[54:55], v[4:5]
	v_mov_b64_e32 v[56:57], v[4:5]
	v_mov_b64_e32 v[58:59], v[4:5]
	v_mov_b64_e32 v[60:61], v[4:5]
	v_mov_b64_e32 v[62:63], v[4:5]
	v_mov_b64_e32 v[64:65], v[4:5]
	v_mov_b64_e32 v[66:67], v[4:5]
	s_waitcnt vmcnt(0) lgkmcnt(0)
	s_barrier
	s_branch .LBB0_1248

; #define WAIT_V8(n) asm volatile("s_waitcnt vmcnt(" #n ")" ::: "memory")
; #define BAR8 __builtin_amdgcn_s_barrier()
; #define G_XF (outp())
; #define G_SS ((float*)(wsp() + OFF_SS))
;     ...
;     STAGE8(SB8(0, 0), Bt, K, bcol, 0); STAGE8(SA8(0, 0), A, lda, brow, 0);
;     STAGE8(SB8(0, 1), Bt, K, bcol + 128, 0); STAGE8(SA8(0, 1), A, lda, brow + 128, 0);
;   }
;   if (wr == 1) BAR8;
;   WAIT_V8(4); BAR8;
;   STAGE8(SB8(1, 0), Bt, K, bcol, 1); STAGE8(SA8(1, 0), A, lda, brow, 1); STAGE8(SB8(1, 1), Bt, K, bcol + 128, 1);
; __global__ void __launch_bounds__(512, 2) mega(Params p) {
;     ...
;     for (int item = bid; item < 4 * 64; item += nb) {
;       const int nt = item >> 6, mt = item & 63;
;       e.ss = nullptr; e.xf = G_XF; e.xb = G_XB; e.ss_out = G_SS;
;       gemm_tile<EPI_RESID, 256, false>(G_ACT, 2816, wb + W_DOWN, 2816, mt * 256, nt * 256, e);
.LBB0_1322:
	s_mov_b32 s0, 24
	s_mov_b32 s0, 25
	s_ashr_i32 s1, s0, 31
	s_lshl_b64 s[0:1], s[0:1], 3
	s_add_u32 s0, s70, s0
	s_addc_u32 s1, s71, s1
	v_readlane_b32 s6, v255, 60
	v_readlane_b32 s7, v255, 61
	s_nop 3
	s_mov_b32 s0, 25
	s_ashr_i32 s1, s0, 31
	s_lshl_b64 s[0:1], s[0:1], 3
	s_add_u32 s0, s70, s0
	s_addc_u32 s1, s71, s1
	s_mov_b32 s2, 25
	v_readlane_b32 s0, v255, 60
	v_readlane_b32 s1, v255, 61
	s_nop 3
	s_ashr_i32 s3, s2, 31
	s_lshl_b64 s[2:3], s[2:3], 3
	s_add_u32 s2, s70, s2
	s_addc_u32 s3, s71, s3
	v_mov_b32_e32 v3, v224
	v_readlane_b32 s2, v255, 60
	v_readlane_b32 s3, v255, 61
	s_nop 3
	s_lshl_b32 s8, s24, 8
	v_bfe_i32 v1, v3, 27, 1
	s_waitcnt vmcnt(10)
	v_lshlrev_b32_e32 v150, 4, v3
	v_lshrrev_b32_e32 v1, 22, v1
	v_add_u32_e32 v1, v150, v1
	v_and_b32_e32 v1, 0xfffffc00, v1
	v_ashrrev_i32_e32 v0, 31, v3
	v_sub_u32_e32 v1, v150, v1
	v_lshrrev_b32_e32 v0, 26, v0
	v_lshrrev_b32_e32 v5, 4, v1
	v_add_u32_e32 v0, v3, v0
	v_bitop3_b32 v6, v5, v1, 32 bitop3:0x6c
	v_ashrrev_i32_e32 v1, 31, v1
	v_ashrrev_i32_e32 v0, 6, v0
	v_lshrrev_b32_e32 v1, 26, v1
	v_lshlrev_b32_e32 v5, 3, v0
	v_add_u32_e32 v1, v6, v1
	v_and_b32_e32 v5, -16, v5
	v_ashrrev_i32_e32 v1, 6, v1
	s_and_b32 s25, s8, 0x3f00
	s_lshl_b32 s8, s24, 2
	v_add_u32_e32 v5, v1, v5
	v_mul_i32_i24_e32 v1, 64, v1
	s_and_b32 s8, s8, 0xffffff00
	v_lshlrev_b32_e32 v0, 5, v0
	v_sub_u32_e32 v1, v6, v1
	v_mov_b32_e32 v15, 1
	s_mul_i32 s12, s8, 0x1600
	v_and_b32_e32 v0, 32, v0
	v_ashrrev_i16_sdwa v1, v15, sext(v1) dst_sel:DWORD dst_unused:UNUSED_PAD src0_sel:DWORD src1_sel:BYTE_0
	s_movk_i32 s27, 0xb00
	s_mul_hi_i32 s9, s8, 0x1600
	s_add_u32 s12, s14, s12
	v_add_u32_sdwa v0, v0, sext(v1) dst_sel:DWORD dst_unused:UNUSED_PAD src0_sel:DWORD src1_sel:WORD_0
	v_mad_i64_i32 v[132:133], s[30:31], v5, s27, 0
	s_addc_u32 s13, s15, s9
	v_lshlrev_b64 v[24:25], 1, v[132:133]
	v_ashrrev_i32_e32 v1, 31, v0
	v_lshl_add_u64 v[8:9], s[12:13], 0, v[24:25]
	v_lshlrev_b64 v[6:7], 1, v[0:1]
	s_waitcnt vmcnt(9)
	v_add_u32_e32 v152, 0x2000, v150
	v_lshl_add_u64 v[10:11], v[8:9], 0, v[6:7]
	v_ashrrev_i32_e32 v8, 31, v152
	v_lshrrev_b32_e32 v8, 22, v8
	v_add_u32_e32 v8, v152, v8
	v_ashrrev_i32_e32 v8, 10, v8
	v_mul_i32_i24_e32 v9, 0x400, v8
	v_sub_u32_e32 v9, v152, v9
	v_lshrrev_b32_e32 v12, 4, v9
	v_bitop3_b32 v9, v12, v9, 32 bitop3:0x6c
	v_ashrrev_i32_e32 v13, 31, v9
	v_add_u32_e32 v151, 0x10000, v150
	v_lshrrev_b32_e32 v13, 26, v13
	v_readfirstlane_b32 s9, v151
	v_lshlrev_b32_e32 v12, 3, v8
	v_add_u32_e32 v13, v9, v13
	s_waitcnt vmcnt(8)
	v_add_u32_e32 v157, 0x12000, v150
	v_mov_b32_e32 v4, v2
	s_mov_b32 m0, s9
	v_and_b32_e32 v12, -16, v12
	v_ashrrev_i32_e32 v14, 6, v13
	v_readfirstlane_b32 s9, v157
	global_load_lds_dwordx4 v[10:11], off
	v_add_u32_e32 v22, v14, v12
	v_and_b32_e32 v12, 0xc0, v13
	s_mov_b32 m0, s9
	s_mul_i32 s9, s25, 0xb00
	v_lshlrev_b32_e32 v8, 5, v8
	v_sub_u32_e32 v9, v9, v12
	v_mad_i64_i32 v[136:137], s[30:31], v22, s27, 0
	s_lshl_b32 s27, s9, 1
	v_and_b32_e32 v8, 32, v8
	v_ashrrev_i16_sdwa v9, v15, sext(v9) dst_sel:DWORD dst_unused:UNUSED_PAD src0_sel:DWORD src1_sel:BYTE_0
	s_waitcnt lgkmcnt(0)
	s_add_u32 s9, s2, s27
	v_add_u32_sdwa v134, v8, sext(v9) dst_sel:DWORD dst_unused:UNUSED_PAD src0_sel:DWORD src1_sel:WORD_0
	v_lshlrev_b64 v[26:27], 1, v[136:137]
	s_addc_u32 s29, s3, 0
	v_lshl_add_u64 v[12:13], s[12:13], 0, v[26:27]
	v_ashrrev_i32_e32 v135, 31, v134
	s_add_u32 s12, s9, 0x2000000
	v_lshlrev_b64 v[8:9], 1, v[134:135]
	s_addc_u32 s13, s29, 0
	v_lshl_add_u64 v[12:13], v[12:13], 0, v[8:9]
	v_lshl_add_u64 v[14:15], s[12:13], 0, v[24:25]
	v_readfirstlane_b32 s30, v150
	global_load_lds_dwordx4 v[12:13], off
	v_lshl_add_u64 v[14:15], v[14:15], 0, v[6:7]
	s_mov_b32 m0, s30
	v_lshl_add_u64 v[16:17], s[12:13], 0, v[26:27]
	v_readfirstlane_b32 s12, v152
	s_or_b32 s30, s8, 0x80
	global_load_lds_dwordx4 v[14:15], off
	s_mov_b32 m0, s12
	s_mul_i32 s12, s30, 0x1600
	s_mul_hi_i32 s13, s30, 0x1600
	s_add_u32 s12, s14, s12
	s_addc_u32 s13, s15, s13
	v_add_u32_e32 v160, 0x14000, v150
	v_lshl_add_u64 v[16:17], v[16:17], 0, v[8:9]
	v_lshl_add_u64 v[18:19], s[12:13], 0, v[24:25]
	v_readfirstlane_b32 s31, v160
	v_add_u32_e32 v161, 0x16000, v150
	global_load_lds_dwordx4 v[16:17], off
	v_lshl_add_u64 v[18:19], v[18:19], 0, v[6:7]
	s_mov_b32 m0, s31
	v_lshl_add_u64 v[20:21], s[12:13], 0, v[26:27]
	v_readfirstlane_b32 s12, v161
	global_load_lds_dwordx4 v[18:19], off
	s_mov_b32 m0, s12
	s_add_u32 s12, s9, 0x20b0000
	s_addc_u32 s13, s29, 0
	v_add_u32_e32 v162, 0x4000, v150
	v_lshl_add_u64 v[20:21], v[20:21], 0, v[8:9]
	v_lshl_add_u64 v[24:25], s[12:13], 0, v[24:25]
	v_readfirstlane_b32 s9, v162
	global_load_lds_dwordx4 v[20:21], off
	v_lshl_add_u64 v[24:25], v[24:25], 0, v[6:7]
	s_mov_b32 m0, s9
	v_add_u32_e32 v163, 0x6000, v150
	global_load_lds_dwordx4 v[24:25], off
	v_lshl_add_u64 v[24:25], s[12:13], 0, v[26:27]
	v_readfirstlane_b32 s9, v163
	v_lshl_add_u64 v[24:25], v[24:25], 0, v[8:9]
	s_mov_b32 m0, s9
	v_ashrrev_i32_e32 v23, 8, v3
	global_load_lds_dwordx4 v[24:25], off
	v_cmp_eq_u32_e32 vcc, 1, v23
	s_and_saveexec_b64 s[12:13], vcc
	s_cbranch_execz .LBB0_1324
	s_barrier

; DI float h_lo(unsigned u) { return (float)__builtin_bit_cast(h2_t, u)[0]; }
; DI float h_hi(unsigned u) { return (float)__builtin_bit_cast(h2_t, u)[1]; }
; #define G_XF (outp())
; __global__ void __launch_bounds__(512, 2) mega(Params p) {
;     ...
;     for (int row = bid * 8 + w; row < NTOK; row += nb * 8) {
;       const uint2* xp = (const uint2*)(G_XB + (size_t)row * DM);
;       float4* op = (float4*)(G_XF + (size_t)row * DM);
;       float4 v[4];
;       float s2 = 0.f;
; #pragma unroll
;       for (int i = 0; i < 4; ++i) {
;         const uint2 u = xp[l + 64 * i];
;         v[i].x = h_lo(u.x); v[i].y = h_hi(u.x);
;         v[i].z = h_lo(u.y); v[i].w = h_hi(u.y);
;         s2 += v[i].x * v[i].x + v[i].y * v[i].y + v[i].z * v[i].z + v[i].w * v[i].w;
;       }
; #pragma unroll
;       for (int o = 32; o; o >>= 1) s2 += __shfl_xor(s2, o);
;       const float rr = rsqrtf(s2 * (1.f / 1024.f) + EPS);
; #pragma unroll
;       for (int i = 0; i < 4; ++i) {
;         const float4 g = gf[l + 64 * i];
;         float4 o4 = {v[i].x * rr * g.x, v[i].y * rr * g.y, v[i].z * rr * g.z, v[i].w * rr * g.w};
;         op[l + 64 * i] = o4;
;       }
.LBB0_1415:
	s_mov_b32 s10, 25
	s_ashr_i32 s11, s10, 31
	s_lshl_b64 s[10:11], s[10:11], 3
	s_add_u32 s10, s70, s10
	s_addc_u32 s11, s71, s11
	v_readlane_b32 s10, v255, 60
	v_readlane_b32 s11, v255, 61
	s_nop 3
	s_mov_b32 s12, 24
	v_cmp_lt_i32_e32 vcc, v8, v1
	s_ashr_i32 s13, s12, 31
	s_waitcnt lgkmcnt(0)
	v_lshl_add_u64 v[16:17], s[10:11], 0, v[4:5]
	global_load_dwordx2 v[20:21], v[16:17], off offset:-1540
	global_load_dwordx2 v[22:23], v[16:17], off offset:-1028
	global_load_dwordx2 v[24:25], v[16:17], off offset:-516
	global_load_dwordx2 v[26:27], v[16:17], off offset:-4
	v_cndmask_b32_e32 v15, v225, v8, vcc
	v_cmp_lt_i32_e32 vcc, v9, v1
	v_lshlrev_b32_e32 v15, 2, v15
	s_lshl_b64 s[10:11], s[12:13], 3
	v_cndmask_b32_e32 v16, v225, v9, vcc
	v_cmp_lt_i32_e32 vcc, v10, v1
	v_lshlrev_b32_e32 v54, 2, v16
	s_add_u32 s10, s70, s10
	v_cndmask_b32_e32 v17, v225, v10, vcc
	v_cmp_lt_i32_e32 vcc, v11, v1
	v_lshlrev_b32_e32 v55, 2, v17
	s_addc_u32 s11, s71, s11
	v_cndmask_b32_e32 v18, v225, v11, vcc
	v_cmp_lt_i32_e32 vcc, v12, v1
	v_lshlrev_b32_e32 v56, 2, v18
	s_load_dwordx2 s[10:11], s[10:11], 0x0
	v_cndmask_b32_e32 v19, v225, v12, vcc
	v_lshlrev_b32_e32 v57, 2, v19
	v_cmp_lt_i32_e32 vcc, v13, v1
	v_add_u32_e32 v0, s0, v0
	v_lshl_add_u64 v[4:5], v[4:5], 0, s[2:3]
	v_cndmask_b32_e32 v28, v225, v13, vcc
	v_lshlrev_b32_e32 v58, 2, v28
	s_waitcnt lgkmcnt(0)
	v_lshl_add_u64 v[28:29], s[10:11], 0, v[6:7]
	v_lshl_add_u64 v[6:7], v[6:7], 0, s[4:5]
	s_waitcnt vmcnt(3)
	v_cvt_f32_f16_sdwa v31, v20 dst_sel:DWORD dst_unused:UNUSED_PAD src0_sel:WORD_1
	s_waitcnt vmcnt(2)
	v_cvt_f32_f16_sdwa v33, v22 dst_sel:DWORD dst_unused:UNUSED_PAD src0_sel:WORD_1
	v_cvt_f32_f16_e32 v30, v20
	v_cvt_f32_f16_e32 v32, v22
	s_waitcnt vmcnt(1)
	v_cvt_f32_f16_sdwa v35, v24 dst_sel:DWORD dst_unused:UNUSED_PAD src0_sel:WORD_1
	s_waitcnt vmcnt(0)
	v_cvt_f32_f16_sdwa v37, v26 dst_sel:DWORD dst_unused:UNUSED_PAD src0_sel:WORD_1
	v_cvt_f32_f16_e32 v20, v21
	v_cvt_f32_f16_e32 v22, v23
	v_cvt_f32_f16_e32 v34, v24
	v_cvt_f32_f16_e32 v36, v26
	v_cvt_f32_f16_sdwa v21, v21 dst_sel:DWORD dst_unused:UNUSED_PAD src0_sel:WORD_1
	v_cvt_f32_f16_sdwa v23, v23 dst_sel:DWORD dst_unused:UNUSED_PAD src0_sel:WORD_1
	v_cvt_f32_f16_e32 v24, v25
	v_cvt_f32_f16_e32 v26, v27
	v_cvt_f32_f16_sdwa v25, v25 dst_sel:DWORD dst_unused:UNUSED_PAD src0_sel:WORD_1
	v_cvt_f32_f16_sdwa v27, v27 dst_sel:DWORD dst_unused:UNUSED_PAD src0_sel:WORD_1
	v_mov_b32_e32 v40, v31
	v_mov_b32_e32 v41, v33
	v_mov_b32_e32 v38, v30
	v_mov_b32_e32 v39, v32
	v_mov_b32_e32 v48, v35
	v_mov_b32_e32 v49, v37
	v_pk_mul_f32 v[40:41], v[40:41], v[40:41]
	v_mov_b32_e32 v42, v20
	v_mov_b32_e32 v43, v22
	v_mov_b32_e32 v46, v34
	v_mov_b32_e32 v47, v36
	v_pk_mul_f32 v[48:49], v[48:49], v[48:49]
	v_pk_fma_f32 v[38:39], v[38:39], v[38:39], v[40:41]
	v_mov_b32_e32 v44, v21
	v_mov_b32_e32 v45, v23
	v_mov_b32_e32 v50, v24
	v_mov_b32_e32 v51, v26
	v_pk_fma_f32 v[40:41], v[46:47], v[46:47], v[48:49]
	v_pk_fma_f32 v[38:39], v[42:43], v[42:43], v[38:39]
	v_mov_b32_e32 v52, v25
	v_mov_b32_e32 v53, v27
	v_pk_fma_f32 v[40:41], v[50:51], v[50:51], v[40:41]
	v_pk_fma_f32 v[38:39], v[44:45], v[44:45], v[38:39]
	v_pk_fma_f32 v[40:41], v[52:53], v[52:53], v[40:41]
	v_add_f32_e32 v38, v38, v39
	v_add_f32_e32 v38, v38, v40
	v_add_f32_e32 v38, v38, v41
	ds_bpermute_b32 v15, v15, v38
	s_waitcnt lgkmcnt(0)
	v_add_f32_e32 v15, v38, v15
	ds_bpermute_b32 v38, v54, v15
	s_waitcnt lgkmcnt(0)
	v_add_f32_e32 v15, v15, v38
	ds_bpermute_b32 v38, v55, v15
	s_waitcnt lgkmcnt(0)
	v_add_f32_e32 v15, v15, v38
	ds_bpermute_b32 v38, v56, v15
	s_waitcnt lgkmcnt(0)
	v_add_f32_e32 v15, v15, v38
	ds_bpermute_b32 v38, v57, v15
	s_waitcnt lgkmcnt(0)
	v_add_f32_e32 v15, v15, v38
	ds_bpermute_b32 v38, v58, v15
	s_waitcnt lgkmcnt(0)
	v_add_f32_e32 v15, v15, v38
	v_fmamk_f32 v15, v15, 0x3a800000, v14
	v_mul_f32_e32 v38, 0x4b800000, v15
	v_cmp_gt_f32_e32 vcc, s1, v15
	s_nop 1
	v_cndmask_b32_e32 v15, v15, v38, vcc
	v_rsq_f32_e32 v15, v15
	s_nop 0
	v_mul_f32_e32 v38, 0x45800000, v15
	v_cndmask_b32_e32 v38, v15, v38, vcc
	v_pk_mul_f32 v[30:31], v[38:39], v[30:31] op_sel_hi:[0,1]
	v_pk_mul_f32 v[20:21], v[38:39], v[20:21] op_sel_hi:[0,1]
	v_pk_mul_f32 v[16:17], v[60:61], v[30:31]
	v_pk_mul_f32 v[18:19], v[62:63], v[20:21]
	global_store_dwordx4 v[28:29], v[16:19], off offset:-3080
	v_pk_mul_f32 v[20:21], v[38:39], v[32:33] op_sel_hi:[0,1]
	v_pk_mul_f32 v[22:23], v[38:39], v[22:23] op_sel_hi:[0,1]
	v_cmp_lt_i32_e32 vcc, s8, v0
	s_or_b64 s[6:7], vcc, s[6:7]
	v_pk_mul_f32 v[76:77], v[64:65], v[20:21]
	v_pk_mul_f32 v[78:79], v[66:67], v[22:23]
	global_store_dwordx4 v[28:29], v[76:79], off offset:-2056
	v_pk_mul_f32 v[20:21], v[38:39], v[34:35] op_sel_hi:[0,1]
	v_pk_mul_f32 v[22:23], v[38:39], v[24:25] op_sel_hi:[0,1]
	v_pk_mul_f32 v[80:81], v[68:69], v[20:21]
	v_pk_mul_f32 v[82:83], v[70:71], v[22:23]
	global_store_dwordx4 v[28:29], v[80:83], off offset:-1032
	v_pk_mul_f32 v[20:21], v[38:39], v[36:37] op_sel_hi:[0,1]
	v_pk_mul_f32 v[22:23], v[38:39], v[26:27] op_sel_hi:[0,1]
	v_pk_mul_f32 v[84:85], v[72:73], v[20:21]
	v_pk_mul_f32 v[86:87], v[74:75], v[22:23]
	global_store_dwordx4 v[28:29], v[84:87], off offset:-8
	s_andn2_b64 exec, exec, s[6:7]
	s_cbranch_execnz .LBB0_1415
